# hand-written RWKV prompt scan block: row-pair packed state, interleaved DPP chains, unrolled 32 steps, y stored once per 16 steps
# speedup vs baseline: 1.0863x; 1.0863x over previous
.LBB0_1345:
	s_or_b64 exec, exec, s[56:57]
	s_and_b32 s0, s63, 0xfffff800
	s_lshl_b32 s30, s72, 5
	s_mul_hi_i32 s1, s0, 0x5200
	s_mulk_i32 s0, 0x5200
	v_and_or_b32 v201, s30, 32, v164
	s_and_b32 s30, s41, 0x780
	s_or_b32 s0, s0, s30
	v_and_or_b32 v5, s65, 32, v164
	s_add_u32 s0, s3, s0
	v_lshlrev_b32_e32 v12, 1, v5
	v_mov_b32_e32 v13, v77
	s_waitcnt lgkmcnt(0)
	s_barrier
	s_addc_u32 s1, s62, s1
	v_lshlrev_b32_e32 v76, 1, v42
	v_lshl_add_u64 v[88:89], s[0:1], 0, v[12:13]
	v_mov_b32_e32 v12, v77
	v_lshlrev_b32_e32 v202, 2, v5
	v_lshl_add_u64 v[84:85], s[22:23], 0, v[76:77]
	v_lshl_add_u64 v[86:87], v[10:11], 2, s[28:29]
	s_mov_b32 s30, 0
	v_mov_b64_e32 v[10:11], v[12:13]
	v_mov_b64_e32 v[16:17], v[12:13]
	v_mov_b64_e32 v[14:15], v[12:13]
	s_branch .LBB0_1348
.LBB0_1347:
	s_or_b64 exec, exec, s[56:57]
	s_waitcnt lgkmcnt(0)
	s_barrier
	s_add_i32 s30, s30, 1
	s_cmp_eq_u32 s30, 64
	v_lshl_add_u64 v[88:89], v[88:89], 0, s[38:39]
	s_cbranch_scc1 .LBB0_1376

.LBB0_1368:
	s_andn2_saveexec_b64 s[56:57], s[56:57]
	s_cbranch_execz .LBB0_1347
	s_cmp_lg_u32 s30, 0
	s_cbranch_scc1 .Lrwp_go
	v_and_b32_e32 v210, 15, v178
	v_lshlrev_b32_e32 v159, 4, v210
	v_lshlrev_b32_e32 v208, 2, v201
	v_add_u32_e32 v208, 0x500, v208
	v_mov_b32_e32 v209, 0x600
	v_mov_b32_e32 v100, 0
	v_mov_b32_e32 v101, 0
	v_mov_b32_e32 v102, 0
	v_mov_b32_e32 v103, 0
	v_mov_b32_e32 v104, 0
	v_mov_b32_e32 v105, 0
	v_mov_b32_e32 v106, 0
	v_mov_b32_e32 v107, 0
.Lrwp_go:
	s_and_b32 s0, s30, 1
	s_mul_i32 s0, s0, 0xc200
	s_movk_i32 s99, 0x5200
	v_add_u32_e32 v156, s0, v159
	v_add_u32_e32 v157, s0, v208
	v_add_u32_e32 v158, s0, v209
	s_mov_b32 s100, 0x52000
	s_mov_b32 s101, 0
	ds_read_b128 v[108:111], v156 offset:0
	ds_read_b128 v[112:115], v156 offset:256
	ds_read_b128 v[120:123], v156 offset:1024
	ds_read_b64 v[124:125], v157 offset:0
	ds_read_b128 v[116:119], v156 offset:768
	ds_read_b64 v[126:127], v158 offset:0
	v_mad_u64_u32 v[160:161], s[58:59], v210, s99, v[88:89]
	s_waitcnt lgkmcnt(0)
	ds_read_b128 v[128:131], v156 offset:1552
	ds_read_b128 v[132:135], v156 offset:1808
	ds_read_b128 v[140:143], v156 offset:2576
	ds_read_b64 v[144:145], v157 offset:1552
	ds_read_b128 v[136:139], v156 offset:2320
	ds_read_b64 v[146:147], v158 offset:1552
	v_pk_mul_f32 v[148:149], v[100:101], v[108:109] op_sel_hi:[1,0]
	v_pk_mul_f32 v[150:151], v[100:101], v[112:113] op_sel_hi:[1,0]
	v_pk_fma_f32 v[148:149], v[102:103], v[108:109], v[148:149] op_sel:[0,1,0]
	v_pk_fma_f32 v[150:151], v[102:103], v[112:113], v[150:151] op_sel:[0,1,0]
	v_pk_fma_f32 v[148:149], v[104:105], v[110:111], v[148:149] op_sel_hi:[1,0,1]
	v_pk_fma_f32 v[150:151], v[104:105], v[114:115], v[150:151] op_sel_hi:[1,0,1]
	v_pk_fma_f32 v[148:149], v[106:107], v[110:111], v[148:149] op_sel:[0,1,0]
	v_pk_fma_f32 v[150:151], v[106:107], v[114:115], v[150:151] op_sel:[0,1,0]
	v_pk_fma_f32 v[100:101], v[124:125], v[120:121], v[100:101] op_sel_hi:[1,0,1]
	v_add_f32_dpp v148, v148, v148 quad_perm:[1,0,3,2] row_mask:0xf bank_mask:0xf bound_ctrl:1
	v_add_f32_dpp v149, v149, v149 quad_perm:[1,0,3,2] row_mask:0xf bank_mask:0xf bound_ctrl:1
	v_add_f32_dpp v150, v150, v150 quad_perm:[1,0,3,2] row_mask:0xf bank_mask:0xf bound_ctrl:1
	v_add_f32_dpp v151, v151, v151 quad_perm:[1,0,3,2] row_mask:0xf bank_mask:0xf bound_ctrl:1
	v_pk_fma_f32 v[102:103], v[124:125], v[120:121], v[102:103] op_sel:[0,1,0]
	v_add_f32_dpp v148, v148, v148 quad_perm:[2,3,0,1] row_mask:0xf bank_mask:0xf bound_ctrl:1
	v_add_f32_dpp v149, v149, v149 quad_perm:[2,3,0,1] row_mask:0xf bank_mask:0xf bound_ctrl:1
	v_add_f32_dpp v150, v150, v150 quad_perm:[2,3,0,1] row_mask:0xf bank_mask:0xf bound_ctrl:1
	v_add_f32_dpp v151, v151, v151 quad_perm:[2,3,0,1] row_mask:0xf bank_mask:0xf bound_ctrl:1
	v_pk_fma_f32 v[104:105], v[124:125], v[122:123], v[104:105] op_sel_hi:[1,0,1]
	v_add_f32_dpp v148, v148, v148 row_half_mirror row_mask:0xf bank_mask:0xf bound_ctrl:1
	v_add_f32_dpp v149, v149, v149 row_half_mirror row_mask:0xf bank_mask:0xf bound_ctrl:1
	v_add_f32_dpp v150, v150, v150 row_half_mirror row_mask:0xf bank_mask:0xf bound_ctrl:1
	v_add_f32_dpp v151, v151, v151 row_half_mirror row_mask:0xf bank_mask:0xf bound_ctrl:1
	v_pk_fma_f32 v[106:107], v[124:125], v[122:123], v[106:107] op_sel:[0,1,0]
	v_add_f32_dpp v148, v148, v148 row_mirror row_mask:0xf bank_mask:0xf bound_ctrl:1
	v_add_f32_dpp v149, v149, v149 row_mirror row_mask:0xf bank_mask:0xf bound_ctrl:1
	v_add_f32_dpp v150, v150, v150 row_mirror row_mask:0xf bank_mask:0xf bound_ctrl:1
	v_pk_fma_f32 v[100:101], v[148:149], v[116:117], v[100:101] op_sel_hi:[1,0,1]
	v_pk_fma_f32 v[102:103], v[148:149], v[116:117], v[102:103] op_sel:[0,1,0]
	v_pk_fma_f32 v[104:105], v[148:149], v[118:119], v[104:105] op_sel_hi:[1,0,1]
	v_pk_fma_f32 v[106:107], v[148:149], v[118:119], v[106:107] op_sel:[0,1,0]
	v_add_f32_dpp v151, v151, v151 row_mirror row_mask:0xf bank_mask:0xf bound_ctrl:1
	v_pk_fma_f32 v[152:153], v[148:149], v[126:127], v[150:151] op_sel_hi:[1,0,1]
	v_pk_fma_f32 v[152:153], v[124:125], v[126:127], v[152:153] op_sel:[0,1,0]
	v_cvt_pk_bf16_f32 v154, v152, v153
	s_waitcnt lgkmcnt(0)
	ds_read_b128 v[108:111], v156 offset:3104
	ds_read_b128 v[112:115], v156 offset:3360
	ds_read_b128 v[120:123], v156 offset:4128
	ds_read_b64 v[124:125], v157 offset:3104
	ds_read_b128 v[116:119], v156 offset:3872
	ds_read_b64 v[126:127], v158 offset:3104
	v_mov_b32_e32 v155, v154
	v_pk_mul_f32 v[148:149], v[100:101], v[128:129] op_sel_hi:[1,0]
	v_pk_mul_f32 v[150:151], v[100:101], v[132:133] op_sel_hi:[1,0]
	v_pk_fma_f32 v[148:149], v[102:103], v[128:129], v[148:149] op_sel:[0,1,0]
	v_pk_fma_f32 v[150:151], v[102:103], v[132:133], v[150:151] op_sel:[0,1,0]
	v_pk_fma_f32 v[148:149], v[104:105], v[130:131], v[148:149] op_sel_hi:[1,0,1]
	v_pk_fma_f32 v[150:151], v[104:105], v[134:135], v[150:151] op_sel_hi:[1,0,1]
	v_pk_fma_f32 v[148:149], v[106:107], v[130:131], v[148:149] op_sel:[0,1,0]
	v_pk_fma_f32 v[150:151], v[106:107], v[134:135], v[150:151] op_sel:[0,1,0]
	v_pk_fma_f32 v[100:101], v[144:145], v[140:141], v[100:101] op_sel_hi:[1,0,1]
	v_add_f32_dpp v148, v148, v148 quad_perm:[1,0,3,2] row_mask:0xf bank_mask:0xf bound_ctrl:1
	v_add_f32_dpp v149, v149, v149 quad_perm:[1,0,3,2] row_mask:0xf bank_mask:0xf bound_ctrl:1
	v_add_f32_dpp v150, v150, v150 quad_perm:[1,0,3,2] row_mask:0xf bank_mask:0xf bound_ctrl:1
	v_add_f32_dpp v151, v151, v151 quad_perm:[1,0,3,2] row_mask:0xf bank_mask:0xf bound_ctrl:1
	v_pk_fma_f32 v[102:103], v[144:145], v[140:141], v[102:103] op_sel:[0,1,0]
	v_add_f32_dpp v148, v148, v148 quad_perm:[2,3,0,1] row_mask:0xf bank_mask:0xf bound_ctrl:1
	v_add_f32_dpp v149, v149, v149 quad_perm:[2,3,0,1] row_mask:0xf bank_mask:0xf bound_ctrl:1
	v_add_f32_dpp v150, v150, v150 quad_perm:[2,3,0,1] row_mask:0xf bank_mask:0xf bound_ctrl:1
	v_add_f32_dpp v151, v151, v151 quad_perm:[2,3,0,1] row_mask:0xf bank_mask:0xf bound_ctrl:1
	v_pk_fma_f32 v[104:105], v[144:145], v[142:143], v[104:105] op_sel_hi:[1,0,1]
	v_add_f32_dpp v148, v148, v148 row_half_mirror row_mask:0xf bank_mask:0xf bound_ctrl:1
	v_add_f32_dpp v149, v149, v149 row_half_mirror row_mask:0xf bank_mask:0xf bound_ctrl:1
	v_add_f32_dpp v150, v150, v150 row_half_mirror row_mask:0xf bank_mask:0xf bound_ctrl:1
	v_add_f32_dpp v151, v151, v151 row_half_mirror row_mask:0xf bank_mask:0xf bound_ctrl:1
	v_pk_fma_f32 v[106:107], v[144:145], v[142:143], v[106:107] op_sel:[0,1,0]
	v_add_f32_dpp v148, v148, v148 row_mirror row_mask:0xf bank_mask:0xf bound_ctrl:1
	v_add_f32_dpp v149, v149, v149 row_mirror row_mask:0xf bank_mask:0xf bound_ctrl:1
	v_add_f32_dpp v150, v150, v150 row_mirror row_mask:0xf bank_mask:0xf bound_ctrl:1
	v_pk_fma_f32 v[100:101], v[148:149], v[136:137], v[100:101] op_sel_hi:[1,0,1]
	v_pk_fma_f32 v[102:103], v[148:149], v[136:137], v[102:103] op_sel:[0,1,0]
	v_pk_fma_f32 v[104:105], v[148:149], v[138:139], v[104:105] op_sel_hi:[1,0,1]
	v_pk_fma_f32 v[106:107], v[148:149], v[138:139], v[106:107] op_sel:[0,1,0]
	v_add_f32_dpp v151, v151, v151 row_mirror row_mask:0xf bank_mask:0xf bound_ctrl:1
	v_pk_fma_f32 v[152:153], v[148:149], v[146:147], v[150:151] op_sel_hi:[1,0,1]
	v_pk_fma_f32 v[152:153], v[144:145], v[146:147], v[152:153] op_sel:[0,1,0]
	v_cvt_pk_bf16_f32 v154, v152, v153
	s_waitcnt lgkmcnt(0)
	ds_read_b128 v[128:131], v156 offset:4656
	ds_read_b128 v[132:135], v156 offset:4912
	ds_read_b128 v[140:143], v156 offset:5680
	ds_read_b64 v[144:145], v157 offset:4656
	ds_read_b128 v[136:139], v156 offset:5424
	ds_read_b64 v[146:147], v158 offset:4656
	v_mov_b32_dpp v155, v154 row_shr:1 row_mask:0xf bank_mask:0xf
	v_pk_mul_f32 v[148:149], v[100:101], v[108:109] op_sel_hi:[1,0]
	v_pk_mul_f32 v[150:151], v[100:101], v[112:113] op_sel_hi:[1,0]
	v_pk_fma_f32 v[148:149], v[102:103], v[108:109], v[148:149] op_sel:[0,1,0]
	v_pk_fma_f32 v[150:151], v[102:103], v[112:113], v[150:151] op_sel:[0,1,0]
	v_pk_fma_f32 v[148:149], v[104:105], v[110:111], v[148:149] op_sel_hi:[1,0,1]
	v_pk_fma_f32 v[150:151], v[104:105], v[114:115], v[150:151] op_sel_hi:[1,0,1]
	v_pk_fma_f32 v[148:149], v[106:107], v[110:111], v[148:149] op_sel:[0,1,0]
	v_pk_fma_f32 v[150:151], v[106:107], v[114:115], v[150:151] op_sel:[0,1,0]
	v_pk_fma_f32 v[100:101], v[124:125], v[120:121], v[100:101] op_sel_hi:[1,0,1]
	v_add_f32_dpp v148, v148, v148 quad_perm:[1,0,3,2] row_mask:0xf bank_mask:0xf bound_ctrl:1
	v_add_f32_dpp v149, v149, v149 quad_perm:[1,0,3,2] row_mask:0xf bank_mask:0xf bound_ctrl:1
	v_add_f32_dpp v150, v150, v150 quad_perm:[1,0,3,2] row_mask:0xf bank_mask:0xf bound_ctrl:1
	v_add_f32_dpp v151, v151, v151 quad_perm:[1,0,3,2] row_mask:0xf bank_mask:0xf bound_ctrl:1
	v_pk_fma_f32 v[102:103], v[124:125], v[120:121], v[102:103] op_sel:[0,1,0]
	v_add_f32_dpp v148, v148, v148 quad_perm:[2,3,0,1] row_mask:0xf bank_mask:0xf bound_ctrl:1
	v_add_f32_dpp v149, v149, v149 quad_perm:[2,3,0,1] row_mask:0xf bank_mask:0xf bound_ctrl:1
	v_add_f32_dpp v150, v150, v150 quad_perm:[2,3,0,1] row_mask:0xf bank_mask:0xf bound_ctrl:1
	v_add_f32_dpp v151, v151, v151 quad_perm:[2,3,0,1] row_mask:0xf bank_mask:0xf bound_ctrl:1
	v_pk_fma_f32 v[104:105], v[124:125], v[122:123], v[104:105] op_sel_hi:[1,0,1]
	v_add_f32_dpp v148, v148, v148 row_half_mirror row_mask:0xf bank_mask:0xf bound_ctrl:1
	v_add_f32_dpp v149, v149, v149 row_half_mirror row_mask:0xf bank_mask:0xf bound_ctrl:1
	v_add_f32_dpp v150, v150, v150 row_half_mirror row_mask:0xf bank_mask:0xf bound_ctrl:1
	v_add_f32_dpp v151, v151, v151 row_half_mirror row_mask:0xf bank_mask:0xf bound_ctrl:1
	v_pk_fma_f32 v[106:107], v[124:125], v[122:123], v[106:107] op_sel:[0,1,0]
	v_add_f32_dpp v148, v148, v148 row_mirror row_mask:0xf bank_mask:0xf bound_ctrl:1
	v_add_f32_dpp v149, v149, v149 row_mirror row_mask:0xf bank_mask:0xf bound_ctrl:1
	v_add_f32_dpp v150, v150, v150 row_mirror row_mask:0xf bank_mask:0xf bound_ctrl:1
	v_pk_fma_f32 v[100:101], v[148:149], v[116:117], v[100:101] op_sel_hi:[1,0,1]
	v_pk_fma_f32 v[102:103], v[148:149], v[116:117], v[102:103] op_sel:[0,1,0]
	v_pk_fma_f32 v[104:105], v[148:149], v[118:119], v[104:105] op_sel_hi:[1,0,1]
	v_pk_fma_f32 v[106:107], v[148:149], v[118:119], v[106:107] op_sel:[0,1,0]
	v_add_f32_dpp v151, v151, v151 row_mirror row_mask:0xf bank_mask:0xf bound_ctrl:1
	v_pk_fma_f32 v[152:153], v[148:149], v[126:127], v[150:151] op_sel_hi:[1,0,1]
	v_pk_fma_f32 v[152:153], v[124:125], v[126:127], v[152:153] op_sel:[0,1,0]
	v_cvt_pk_bf16_f32 v154, v152, v153
	s_waitcnt lgkmcnt(0)
	ds_read_b128 v[108:111], v156 offset:6208
	ds_read_b128 v[112:115], v156 offset:6464
	ds_read_b128 v[120:123], v156 offset:7232
	ds_read_b64 v[124:125], v157 offset:6208
	ds_read_b128 v[116:119], v156 offset:6976
	ds_read_b64 v[126:127], v158 offset:6208
	v_mov_b32_dpp v155, v154 row_shr:2 row_mask:0xf bank_mask:0xf
	v_pk_mul_f32 v[148:149], v[100:101], v[128:129] op_sel_hi:[1,0]
	v_pk_mul_f32 v[150:151], v[100:101], v[132:133] op_sel_hi:[1,0]
	v_pk_fma_f32 v[148:149], v[102:103], v[128:129], v[148:149] op_sel:[0,1,0]
	v_pk_fma_f32 v[150:151], v[102:103], v[132:133], v[150:151] op_sel:[0,1,0]
	v_pk_fma_f32 v[148:149], v[104:105], v[130:131], v[148:149] op_sel_hi:[1,0,1]
	v_pk_fma_f32 v[150:151], v[104:105], v[134:135], v[150:151] op_sel_hi:[1,0,1]
	v_pk_fma_f32 v[148:149], v[106:107], v[130:131], v[148:149] op_sel:[0,1,0]
	v_pk_fma_f32 v[150:151], v[106:107], v[134:135], v[150:151] op_sel:[0,1,0]
	v_pk_fma_f32 v[100:101], v[144:145], v[140:141], v[100:101] op_sel_hi:[1,0,1]
	v_add_f32_dpp v148, v148, v148 quad_perm:[1,0,3,2] row_mask:0xf bank_mask:0xf bound_ctrl:1
	v_add_f32_dpp v149, v149, v149 quad_perm:[1,0,3,2] row_mask:0xf bank_mask:0xf bound_ctrl:1
	v_add_f32_dpp v150, v150, v150 quad_perm:[1,0,3,2] row_mask:0xf bank_mask:0xf bound_ctrl:1
	v_add_f32_dpp v151, v151, v151 quad_perm:[1,0,3,2] row_mask:0xf bank_mask:0xf bound_ctrl:1
	v_pk_fma_f32 v[102:103], v[144:145], v[140:141], v[102:103] op_sel:[0,1,0]
	v_add_f32_dpp v148, v148, v148 quad_perm:[2,3,0,1] row_mask:0xf bank_mask:0xf bound_ctrl:1
	v_add_f32_dpp v149, v149, v149 quad_perm:[2,3,0,1] row_mask:0xf bank_mask:0xf bound_ctrl:1
	v_add_f32_dpp v150, v150, v150 quad_perm:[2,3,0,1] row_mask:0xf bank_mask:0xf bound_ctrl:1
	v_add_f32_dpp v151, v151, v151 quad_perm:[2,3,0,1] row_mask:0xf bank_mask:0xf bound_ctrl:1
	v_pk_fma_f32 v[104:105], v[144:145], v[142:143], v[104:105] op_sel_hi:[1,0,1]
	v_add_f32_dpp v148, v148, v148 row_half_mirror row_mask:0xf bank_mask:0xf bound_ctrl:1
	v_add_f32_dpp v149, v149, v149 row_half_mirror row_mask:0xf bank_mask:0xf bound_ctrl:1
	v_add_f32_dpp v150, v150, v150 row_half_mirror row_mask:0xf bank_mask:0xf bound_ctrl:1
	v_add_f32_dpp v151, v151, v151 row_half_mirror row_mask:0xf bank_mask:0xf bound_ctrl:1
	v_pk_fma_f32 v[106:107], v[144:145], v[142:143], v[106:107] op_sel:[0,1,0]
	v_add_f32_dpp v148, v148, v148 row_mirror row_mask:0xf bank_mask:0xf bound_ctrl:1
	v_add_f32_dpp v149, v149, v149 row_mirror row_mask:0xf bank_mask:0xf bound_ctrl:1
	v_add_f32_dpp v150, v150, v150 row_mirror row_mask:0xf bank_mask:0xf bound_ctrl:1
	v_pk_fma_f32 v[100:101], v[148:149], v[136:137], v[100:101] op_sel_hi:[1,0,1]
	v_pk_fma_f32 v[102:103], v[148:149], v[136:137], v[102:103] op_sel:[0,1,0]
	v_pk_fma_f32 v[104:105], v[148:149], v[138:139], v[104:105] op_sel_hi:[1,0,1]
	v_pk_fma_f32 v[106:107], v[148:149], v[138:139], v[106:107] op_sel:[0,1,0]
	v_add_f32_dpp v151, v151, v151 row_mirror row_mask:0xf bank_mask:0xf bound_ctrl:1
	v_pk_fma_f32 v[152:153], v[148:149], v[146:147], v[150:151] op_sel_hi:[1,0,1]
	v_pk_fma_f32 v[152:153], v[144:145], v[146:147], v[152:153] op_sel:[0,1,0]
	v_cvt_pk_bf16_f32 v154, v152, v153
	s_waitcnt lgkmcnt(0)
	ds_read_b128 v[128:131], v156 offset:7760
	ds_read_b128 v[132:135], v156 offset:8016
	ds_read_b128 v[140:143], v156 offset:8784
	ds_read_b64 v[144:145], v157 offset:7760
	ds_read_b128 v[136:139], v156 offset:8528
	ds_read_b64 v[146:147], v158 offset:7760
	v_mov_b32_dpp v155, v154 row_shr:3 row_mask:0xf bank_mask:0xf
	v_pk_mul_f32 v[148:149], v[100:101], v[108:109] op_sel_hi:[1,0]
	v_pk_mul_f32 v[150:151], v[100:101], v[112:113] op_sel_hi:[1,0]
	v_pk_fma_f32 v[148:149], v[102:103], v[108:109], v[148:149] op_sel:[0,1,0]
	v_pk_fma_f32 v[150:151], v[102:103], v[112:113], v[150:151] op_sel:[0,1,0]
	v_pk_fma_f32 v[148:149], v[104:105], v[110:111], v[148:149] op_sel_hi:[1,0,1]
	v_pk_fma_f32 v[150:151], v[104:105], v[114:115], v[150:151] op_sel_hi:[1,0,1]
	v_pk_fma_f32 v[148:149], v[106:107], v[110:111], v[148:149] op_sel:[0,1,0]
	v_pk_fma_f32 v[150:151], v[106:107], v[114:115], v[150:151] op_sel:[0,1,0]
	v_pk_fma_f32 v[100:101], v[124:125], v[120:121], v[100:101] op_sel_hi:[1,0,1]
	v_add_f32_dpp v148, v148, v148 quad_perm:[1,0,3,2] row_mask:0xf bank_mask:0xf bound_ctrl:1
	v_add_f32_dpp v149, v149, v149 quad_perm:[1,0,3,2] row_mask:0xf bank_mask:0xf bound_ctrl:1
	v_add_f32_dpp v150, v150, v150 quad_perm:[1,0,3,2] row_mask:0xf bank_mask:0xf bound_ctrl:1
	v_add_f32_dpp v151, v151, v151 quad_perm:[1,0,3,2] row_mask:0xf bank_mask:0xf bound_ctrl:1
	v_pk_fma_f32 v[102:103], v[124:125], v[120:121], v[102:103] op_sel:[0,1,0]
	v_add_f32_dpp v148, v148, v148 quad_perm:[2,3,0,1] row_mask:0xf bank_mask:0xf bound_ctrl:1
	v_add_f32_dpp v149, v149, v149 quad_perm:[2,3,0,1] row_mask:0xf bank_mask:0xf bound_ctrl:1
	v_add_f32_dpp v150, v150, v150 quad_perm:[2,3,0,1] row_mask:0xf bank_mask:0xf bound_ctrl:1
	v_add_f32_dpp v151, v151, v151 quad_perm:[2,3,0,1] row_mask:0xf bank_mask:0xf bound_ctrl:1
	v_pk_fma_f32 v[104:105], v[124:125], v[122:123], v[104:105] op_sel_hi:[1,0,1]
	v_add_f32_dpp v148, v148, v148 row_half_mirror row_mask:0xf bank_mask:0xf bound_ctrl:1
	v_add_f32_dpp v149, v149, v149 row_half_mirror row_mask:0xf bank_mask:0xf bound_ctrl:1
	v_add_f32_dpp v150, v150, v150 row_half_mirror row_mask:0xf bank_mask:0xf bound_ctrl:1
	v_add_f32_dpp v151, v151, v151 row_half_mirror row_mask:0xf bank_mask:0xf bound_ctrl:1
	v_pk_fma_f32 v[106:107], v[124:125], v[122:123], v[106:107] op_sel:[0,1,0]
	v_add_f32_dpp v148, v148, v148 row_mirror row_mask:0xf bank_mask:0xf bound_ctrl:1
	v_add_f32_dpp v149, v149, v149 row_mirror row_mask:0xf bank_mask:0xf bound_ctrl:1
	v_add_f32_dpp v150, v150, v150 row_mirror row_mask:0xf bank_mask:0xf bound_ctrl:1
	v_pk_fma_f32 v[100:101], v[148:149], v[116:117], v[100:101] op_sel_hi:[1,0,1]
	v_pk_fma_f32 v[102:103], v[148:149], v[116:117], v[102:103] op_sel:[0,1,0]
	v_pk_fma_f32 v[104:105], v[148:149], v[118:119], v[104:105] op_sel_hi:[1,0,1]
	v_pk_fma_f32 v[106:107], v[148:149], v[118:119], v[106:107] op_sel:[0,1,0]
	v_add_f32_dpp v151, v151, v151 row_mirror row_mask:0xf bank_mask:0xf bound_ctrl:1
	v_pk_fma_f32 v[152:153], v[148:149], v[126:127], v[150:151] op_sel_hi:[1,0,1]
	v_pk_fma_f32 v[152:153], v[124:125], v[126:127], v[152:153] op_sel:[0,1,0]
	v_cvt_pk_bf16_f32 v154, v152, v153
	s_waitcnt lgkmcnt(0)
	ds_read_b128 v[108:111], v156 offset:9312
	ds_read_b128 v[112:115], v156 offset:9568
	ds_read_b128 v[120:123], v156 offset:10336
	ds_read_b64 v[124:125], v157 offset:9312
	ds_read_b128 v[116:119], v156 offset:10080
	ds_read_b64 v[126:127], v158 offset:9312
	v_mov_b32_dpp v155, v154 row_shr:4 row_mask:0xf bank_mask:0xf
	v_pk_mul_f32 v[148:149], v[100:101], v[128:129] op_sel_hi:[1,0]
	v_pk_mul_f32 v[150:151], v[100:101], v[132:133] op_sel_hi:[1,0]
	v_pk_fma_f32 v[148:149], v[102:103], v[128:129], v[148:149] op_sel:[0,1,0]
	v_pk_fma_f32 v[150:151], v[102:103], v[132:133], v[150:151] op_sel:[0,1,0]
	v_pk_fma_f32 v[148:149], v[104:105], v[130:131], v[148:149] op_sel_hi:[1,0,1]
	v_pk_fma_f32 v[150:151], v[104:105], v[134:135], v[150:151] op_sel_hi:[1,0,1]
	v_pk_fma_f32 v[148:149], v[106:107], v[130:131], v[148:149] op_sel:[0,1,0]
	v_pk_fma_f32 v[150:151], v[106:107], v[134:135], v[150:151] op_sel:[0,1,0]
	v_pk_fma_f32 v[100:101], v[144:145], v[140:141], v[100:101] op_sel_hi:[1,0,1]
	v_add_f32_dpp v148, v148, v148 quad_perm:[1,0,3,2] row_mask:0xf bank_mask:0xf bound_ctrl:1
	v_add_f32_dpp v149, v149, v149 quad_perm:[1,0,3,2] row_mask:0xf bank_mask:0xf bound_ctrl:1
	v_add_f32_dpp v150, v150, v150 quad_perm:[1,0,3,2] row_mask:0xf bank_mask:0xf bound_ctrl:1
	v_add_f32_dpp v151, v151, v151 quad_perm:[1,0,3,2] row_mask:0xf bank_mask:0xf bound_ctrl:1
	v_pk_fma_f32 v[102:103], v[144:145], v[140:141], v[102:103] op_sel:[0,1,0]
	v_add_f32_dpp v148, v148, v148 quad_perm:[2,3,0,1] row_mask:0xf bank_mask:0xf bound_ctrl:1
	v_add_f32_dpp v149, v149, v149 quad_perm:[2,3,0,1] row_mask:0xf bank_mask:0xf bound_ctrl:1
	v_add_f32_dpp v150, v150, v150 quad_perm:[2,3,0,1] row_mask:0xf bank_mask:0xf bound_ctrl:1
	v_add_f32_dpp v151, v151, v151 quad_perm:[2,3,0,1] row_mask:0xf bank_mask:0xf bound_ctrl:1
	v_pk_fma_f32 v[104:105], v[144:145], v[142:143], v[104:105] op_sel_hi:[1,0,1]
	v_add_f32_dpp v148, v148, v148 row_half_mirror row_mask:0xf bank_mask:0xf bound_ctrl:1
	v_add_f32_dpp v149, v149, v149 row_half_mirror row_mask:0xf bank_mask:0xf bound_ctrl:1
	v_add_f32_dpp v150, v150, v150 row_half_mirror row_mask:0xf bank_mask:0xf bound_ctrl:1
	v_add_f32_dpp v151, v151, v151 row_half_mirror row_mask:0xf bank_mask:0xf bound_ctrl:1
	v_pk_fma_f32 v[106:107], v[144:145], v[142:143], v[106:107] op_sel:[0,1,0]
	v_add_f32_dpp v148, v148, v148 row_mirror row_mask:0xf bank_mask:0xf bound_ctrl:1
	v_add_f32_dpp v149, v149, v149 row_mirror row_mask:0xf bank_mask:0xf bound_ctrl:1
	v_add_f32_dpp v150, v150, v150 row_mirror row_mask:0xf bank_mask:0xf bound_ctrl:1
	v_pk_fma_f32 v[100:101], v[148:149], v[136:137], v[100:101] op_sel_hi:[1,0,1]
	v_pk_fma_f32 v[102:103], v[148:149], v[136:137], v[102:103] op_sel:[0,1,0]
	v_pk_fma_f32 v[104:105], v[148:149], v[138:139], v[104:105] op_sel_hi:[1,0,1]
	v_pk_fma_f32 v[106:107], v[148:149], v[138:139], v[106:107] op_sel:[0,1,0]
	v_add_f32_dpp v151, v151, v151 row_mirror row_mask:0xf bank_mask:0xf bound_ctrl:1
	v_pk_fma_f32 v[152:153], v[148:149], v[146:147], v[150:151] op_sel_hi:[1,0,1]
	v_pk_fma_f32 v[152:153], v[144:145], v[146:147], v[152:153] op_sel:[0,1,0]
	v_cvt_pk_bf16_f32 v154, v152, v153
	s_waitcnt lgkmcnt(0)
	ds_read_b128 v[128:131], v156 offset:10864
	ds_read_b128 v[132:135], v156 offset:11120
	ds_read_b128 v[140:143], v156 offset:11888
	ds_read_b64 v[144:145], v157 offset:10864
	ds_read_b128 v[136:139], v156 offset:11632
	ds_read_b64 v[146:147], v158 offset:10864
	v_mov_b32_dpp v155, v154 row_shr:5 row_mask:0xf bank_mask:0xf
	v_pk_mul_f32 v[148:149], v[100:101], v[108:109] op_sel_hi:[1,0]
	v_pk_mul_f32 v[150:151], v[100:101], v[112:113] op_sel_hi:[1,0]
	v_pk_fma_f32 v[148:149], v[102:103], v[108:109], v[148:149] op_sel:[0,1,0]
	v_pk_fma_f32 v[150:151], v[102:103], v[112:113], v[150:151] op_sel:[0,1,0]
	v_pk_fma_f32 v[148:149], v[104:105], v[110:111], v[148:149] op_sel_hi:[1,0,1]
	v_pk_fma_f32 v[150:151], v[104:105], v[114:115], v[150:151] op_sel_hi:[1,0,1]
	v_pk_fma_f32 v[148:149], v[106:107], v[110:111], v[148:149] op_sel:[0,1,0]
	v_pk_fma_f32 v[150:151], v[106:107], v[114:115], v[150:151] op_sel:[0,1,0]
	v_pk_fma_f32 v[100:101], v[124:125], v[120:121], v[100:101] op_sel_hi:[1,0,1]
	v_add_f32_dpp v148, v148, v148 quad_perm:[1,0,3,2] row_mask:0xf bank_mask:0xf bound_ctrl:1
	v_add_f32_dpp v149, v149, v149 quad_perm:[1,0,3,2] row_mask:0xf bank_mask:0xf bound_ctrl:1
	v_add_f32_dpp v150, v150, v150 quad_perm:[1,0,3,2] row_mask:0xf bank_mask:0xf bound_ctrl:1
	v_add_f32_dpp v151, v151, v151 quad_perm:[1,0,3,2] row_mask:0xf bank_mask:0xf bound_ctrl:1
	v_pk_fma_f32 v[102:103], v[124:125], v[120:121], v[102:103] op_sel:[0,1,0]
	v_add_f32_dpp v148, v148, v148 quad_perm:[2,3,0,1] row_mask:0xf bank_mask:0xf bound_ctrl:1
	v_add_f32_dpp v149, v149, v149 quad_perm:[2,3,0,1] row_mask:0xf bank_mask:0xf bound_ctrl:1
	v_add_f32_dpp v150, v150, v150 quad_perm:[2,3,0,1] row_mask:0xf bank_mask:0xf bound_ctrl:1
	v_add_f32_dpp v151, v151, v151 quad_perm:[2,3,0,1] row_mask:0xf bank_mask:0xf bound_ctrl:1
	v_pk_fma_f32 v[104:105], v[124:125], v[122:123], v[104:105] op_sel_hi:[1,0,1]
	v_add_f32_dpp v148, v148, v148 row_half_mirror row_mask:0xf bank_mask:0xf bound_ctrl:1
	v_add_f32_dpp v149, v149, v149 row_half_mirror row_mask:0xf bank_mask:0xf bound_ctrl:1
	v_add_f32_dpp v150, v150, v150 row_half_mirror row_mask:0xf bank_mask:0xf bound_ctrl:1
	v_add_f32_dpp v151, v151, v151 row_half_mirror row_mask:0xf bank_mask:0xf bound_ctrl:1
	v_pk_fma_f32 v[106:107], v[124:125], v[122:123], v[106:107] op_sel:[0,1,0]
	v_add_f32_dpp v148, v148, v148 row_mirror row_mask:0xf bank_mask:0xf bound_ctrl:1
	v_add_f32_dpp v149, v149, v149 row_mirror row_mask:0xf bank_mask:0xf bound_ctrl:1
	v_add_f32_dpp v150, v150, v150 row_mirror row_mask:0xf bank_mask:0xf bound_ctrl:1
	v_pk_fma_f32 v[100:101], v[148:149], v[116:117], v[100:101] op_sel_hi:[1,0,1]
	v_pk_fma_f32 v[102:103], v[148:149], v[116:117], v[102:103] op_sel:[0,1,0]
	v_pk_fma_f32 v[104:105], v[148:149], v[118:119], v[104:105] op_sel_hi:[1,0,1]
	v_pk_fma_f32 v[106:107], v[148:149], v[118:119], v[106:107] op_sel:[0,1,0]
	v_add_f32_dpp v151, v151, v151 row_mirror row_mask:0xf bank_mask:0xf bound_ctrl:1
	v_pk_fma_f32 v[152:153], v[148:149], v[126:127], v[150:151] op_sel_hi:[1,0,1]
	v_pk_fma_f32 v[152:153], v[124:125], v[126:127], v[152:153] op_sel:[0,1,0]
	v_cvt_pk_bf16_f32 v154, v152, v153
	s_waitcnt lgkmcnt(0)
	ds_read_b128 v[108:111], v156 offset:12416
	ds_read_b128 v[112:115], v156 offset:12672
	ds_read_b128 v[120:123], v156 offset:13440
	ds_read_b64 v[124:125], v157 offset:12416
	ds_read_b128 v[116:119], v156 offset:13184
	ds_read_b64 v[126:127], v158 offset:12416
	v_mov_b32_dpp v155, v154 row_shr:6 row_mask:0xf bank_mask:0xf
	v_pk_mul_f32 v[148:149], v[100:101], v[128:129] op_sel_hi:[1,0]
	v_pk_mul_f32 v[150:151], v[100:101], v[132:133] op_sel_hi:[1,0]
	v_pk_fma_f32 v[148:149], v[102:103], v[128:129], v[148:149] op_sel:[0,1,0]
	v_pk_fma_f32 v[150:151], v[102:103], v[132:133], v[150:151] op_sel:[0,1,0]
	v_pk_fma_f32 v[148:149], v[104:105], v[130:131], v[148:149] op_sel_hi:[1,0,1]
	v_pk_fma_f32 v[150:151], v[104:105], v[134:135], v[150:151] op_sel_hi:[1,0,1]
	v_pk_fma_f32 v[148:149], v[106:107], v[130:131], v[148:149] op_sel:[0,1,0]
	v_pk_fma_f32 v[150:151], v[106:107], v[134:135], v[150:151] op_sel:[0,1,0]
	v_pk_fma_f32 v[100:101], v[144:145], v[140:141], v[100:101] op_sel_hi:[1,0,1]
	v_add_f32_dpp v148, v148, v148 quad_perm:[1,0,3,2] row_mask:0xf bank_mask:0xf bound_ctrl:1
	v_add_f32_dpp v149, v149, v149 quad_perm:[1,0,3,2] row_mask:0xf bank_mask:0xf bound_ctrl:1
	v_add_f32_dpp v150, v150, v150 quad_perm:[1,0,3,2] row_mask:0xf bank_mask:0xf bound_ctrl:1
	v_add_f32_dpp v151, v151, v151 quad_perm:[1,0,3,2] row_mask:0xf bank_mask:0xf bound_ctrl:1
	v_pk_fma_f32 v[102:103], v[144:145], v[140:141], v[102:103] op_sel:[0,1,0]
	v_add_f32_dpp v148, v148, v148 quad_perm:[2,3,0,1] row_mask:0xf bank_mask:0xf bound_ctrl:1
	v_add_f32_dpp v149, v149, v149 quad_perm:[2,3,0,1] row_mask:0xf bank_mask:0xf bound_ctrl:1
	v_add_f32_dpp v150, v150, v150 quad_perm:[2,3,0,1] row_mask:0xf bank_mask:0xf bound_ctrl:1
	v_add_f32_dpp v151, v151, v151 quad_perm:[2,3,0,1] row_mask:0xf bank_mask:0xf bound_ctrl:1
	v_pk_fma_f32 v[104:105], v[144:145], v[142:143], v[104:105] op_sel_hi:[1,0,1]
	v_add_f32_dpp v148, v148, v148 row_half_mirror row_mask:0xf bank_mask:0xf bound_ctrl:1
	v_add_f32_dpp v149, v149, v149 row_half_mirror row_mask:0xf bank_mask:0xf bound_ctrl:1
	v_add_f32_dpp v150, v150, v150 row_half_mirror row_mask:0xf bank_mask:0xf bound_ctrl:1
	v_add_f32_dpp v151, v151, v151 row_half_mirror row_mask:0xf bank_mask:0xf bound_ctrl:1
	v_pk_fma_f32 v[106:107], v[144:145], v[142:143], v[106:107] op_sel:[0,1,0]
	v_add_f32_dpp v148, v148, v148 row_mirror row_mask:0xf bank_mask:0xf bound_ctrl:1
	v_add_f32_dpp v149, v149, v149 row_mirror row_mask:0xf bank_mask:0xf bound_ctrl:1
	v_add_f32_dpp v150, v150, v150 row_mirror row_mask:0xf bank_mask:0xf bound_ctrl:1
	v_pk_fma_f32 v[100:101], v[148:149], v[136:137], v[100:101] op_sel_hi:[1,0,1]
	v_pk_fma_f32 v[102:103], v[148:149], v[136:137], v[102:103] op_sel:[0,1,0]
	v_pk_fma_f32 v[104:105], v[148:149], v[138:139], v[104:105] op_sel_hi:[1,0,1]
	v_pk_fma_f32 v[106:107], v[148:149], v[138:139], v[106:107] op_sel:[0,1,0]
	v_add_f32_dpp v151, v151, v151 row_mirror row_mask:0xf bank_mask:0xf bound_ctrl:1
	v_pk_fma_f32 v[152:153], v[148:149], v[146:147], v[150:151] op_sel_hi:[1,0,1]
	v_pk_fma_f32 v[152:153], v[144:145], v[146:147], v[152:153] op_sel:[0,1,0]
	v_cvt_pk_bf16_f32 v154, v152, v153
	s_waitcnt lgkmcnt(0)
	ds_read_b128 v[128:131], v156 offset:13968
	ds_read_b128 v[132:135], v156 offset:14224
	ds_read_b128 v[140:143], v156 offset:14992
	ds_read_b64 v[144:145], v157 offset:13968
	ds_read_b128 v[136:139], v156 offset:14736
	ds_read_b64 v[146:147], v158 offset:13968
	v_mov_b32_dpp v155, v154 row_shr:7 row_mask:0xf bank_mask:0xf
	v_pk_mul_f32 v[148:149], v[100:101], v[108:109] op_sel_hi:[1,0]
	v_pk_mul_f32 v[150:151], v[100:101], v[112:113] op_sel_hi:[1,0]
	v_pk_fma_f32 v[148:149], v[102:103], v[108:109], v[148:149] op_sel:[0,1,0]
	v_pk_fma_f32 v[150:151], v[102:103], v[112:113], v[150:151] op_sel:[0,1,0]
	v_pk_fma_f32 v[148:149], v[104:105], v[110:111], v[148:149] op_sel_hi:[1,0,1]
	v_pk_fma_f32 v[150:151], v[104:105], v[114:115], v[150:151] op_sel_hi:[1,0,1]
	v_pk_fma_f32 v[148:149], v[106:107], v[110:111], v[148:149] op_sel:[0,1,0]
	v_pk_fma_f32 v[150:151], v[106:107], v[114:115], v[150:151] op_sel:[0,1,0]
	v_pk_fma_f32 v[100:101], v[124:125], v[120:121], v[100:101] op_sel_hi:[1,0,1]
	v_add_f32_dpp v148, v148, v148 quad_perm:[1,0,3,2] row_mask:0xf bank_mask:0xf bound_ctrl:1
	v_add_f32_dpp v149, v149, v149 quad_perm:[1,0,3,2] row_mask:0xf bank_mask:0xf bound_ctrl:1
	v_add_f32_dpp v150, v150, v150 quad_perm:[1,0,3,2] row_mask:0xf bank_mask:0xf bound_ctrl:1
	v_add_f32_dpp v151, v151, v151 quad_perm:[1,0,3,2] row_mask:0xf bank_mask:0xf bound_ctrl:1
	v_pk_fma_f32 v[102:103], v[124:125], v[120:121], v[102:103] op_sel:[0,1,0]
	v_add_f32_dpp v148, v148, v148 quad_perm:[2,3,0,1] row_mask:0xf bank_mask:0xf bound_ctrl:1
	v_add_f32_dpp v149, v149, v149 quad_perm:[2,3,0,1] row_mask:0xf bank_mask:0xf bound_ctrl:1
	v_add_f32_dpp v150, v150, v150 quad_perm:[2,3,0,1] row_mask:0xf bank_mask:0xf bound_ctrl:1
	v_add_f32_dpp v151, v151, v151 quad_perm:[2,3,0,1] row_mask:0xf bank_mask:0xf bound_ctrl:1
	v_pk_fma_f32 v[104:105], v[124:125], v[122:123], v[104:105] op_sel_hi:[1,0,1]
	v_add_f32_dpp v148, v148, v148 row_half_mirror row_mask:0xf bank_mask:0xf bound_ctrl:1
	v_add_f32_dpp v149, v149, v149 row_half_mirror row_mask:0xf bank_mask:0xf bound_ctrl:1
	v_add_f32_dpp v150, v150, v150 row_half_mirror row_mask:0xf bank_mask:0xf bound_ctrl:1
	v_add_f32_dpp v151, v151, v151 row_half_mirror row_mask:0xf bank_mask:0xf bound_ctrl:1
	v_pk_fma_f32 v[106:107], v[124:125], v[122:123], v[106:107] op_sel:[0,1,0]
	v_add_f32_dpp v148, v148, v148 row_mirror row_mask:0xf bank_mask:0xf bound_ctrl:1
	v_add_f32_dpp v149, v149, v149 row_mirror row_mask:0xf bank_mask:0xf bound_ctrl:1
	v_add_f32_dpp v150, v150, v150 row_mirror row_mask:0xf bank_mask:0xf bound_ctrl:1
	v_pk_fma_f32 v[100:101], v[148:149], v[116:117], v[100:101] op_sel_hi:[1,0,1]
	v_pk_fma_f32 v[102:103], v[148:149], v[116:117], v[102:103] op_sel:[0,1,0]
	v_pk_fma_f32 v[104:105], v[148:149], v[118:119], v[104:105] op_sel_hi:[1,0,1]
	v_pk_fma_f32 v[106:107], v[148:149], v[118:119], v[106:107] op_sel:[0,1,0]
	v_add_f32_dpp v151, v151, v151 row_mirror row_mask:0xf bank_mask:0xf bound_ctrl:1
	v_pk_fma_f32 v[152:153], v[148:149], v[126:127], v[150:151] op_sel_hi:[1,0,1]
	v_pk_fma_f32 v[152:153], v[124:125], v[126:127], v[152:153] op_sel:[0,1,0]
	v_cvt_pk_bf16_f32 v154, v152, v153
	s_waitcnt lgkmcnt(0)
	ds_read_b128 v[108:111], v156 offset:15520
	ds_read_b128 v[112:115], v156 offset:15776
	ds_read_b128 v[120:123], v156 offset:16544
	ds_read_b64 v[124:125], v157 offset:15520
	ds_read_b128 v[116:119], v156 offset:16288
	ds_read_b64 v[126:127], v158 offset:15520
	v_mov_b32_dpp v155, v154 row_shr:8 row_mask:0xf bank_mask:0xf
	v_pk_mul_f32 v[148:149], v[100:101], v[128:129] op_sel_hi:[1,0]
	v_pk_mul_f32 v[150:151], v[100:101], v[132:133] op_sel_hi:[1,0]
	v_pk_fma_f32 v[148:149], v[102:103], v[128:129], v[148:149] op_sel:[0,1,0]
	v_pk_fma_f32 v[150:151], v[102:103], v[132:133], v[150:151] op_sel:[0,1,0]
	v_pk_fma_f32 v[148:149], v[104:105], v[130:131], v[148:149] op_sel_hi:[1,0,1]
	v_pk_fma_f32 v[150:151], v[104:105], v[134:135], v[150:151] op_sel_hi:[1,0,1]
	v_pk_fma_f32 v[148:149], v[106:107], v[130:131], v[148:149] op_sel:[0,1,0]
	v_pk_fma_f32 v[150:151], v[106:107], v[134:135], v[150:151] op_sel:[0,1,0]
	v_pk_fma_f32 v[100:101], v[144:145], v[140:141], v[100:101] op_sel_hi:[1,0,1]
	v_add_f32_dpp v148, v148, v148 quad_perm:[1,0,3,2] row_mask:0xf bank_mask:0xf bound_ctrl:1
	v_add_f32_dpp v149, v149, v149 quad_perm:[1,0,3,2] row_mask:0xf bank_mask:0xf bound_ctrl:1
	v_add_f32_dpp v150, v150, v150 quad_perm:[1,0,3,2] row_mask:0xf bank_mask:0xf bound_ctrl:1
	v_add_f32_dpp v151, v151, v151 quad_perm:[1,0,3,2] row_mask:0xf bank_mask:0xf bound_ctrl:1
	v_pk_fma_f32 v[102:103], v[144:145], v[140:141], v[102:103] op_sel:[0,1,0]
	v_add_f32_dpp v148, v148, v148 quad_perm:[2,3,0,1] row_mask:0xf bank_mask:0xf bound_ctrl:1
	v_add_f32_dpp v149, v149, v149 quad_perm:[2,3,0,1] row_mask:0xf bank_mask:0xf bound_ctrl:1
	v_add_f32_dpp v150, v150, v150 quad_perm:[2,3,0,1] row_mask:0xf bank_mask:0xf bound_ctrl:1
	v_add_f32_dpp v151, v151, v151 quad_perm:[2,3,0,1] row_mask:0xf bank_mask:0xf bound_ctrl:1
	v_pk_fma_f32 v[104:105], v[144:145], v[142:143], v[104:105] op_sel_hi:[1,0,1]
	v_add_f32_dpp v148, v148, v148 row_half_mirror row_mask:0xf bank_mask:0xf bound_ctrl:1
	v_add_f32_dpp v149, v149, v149 row_half_mirror row_mask:0xf bank_mask:0xf bound_ctrl:1
	v_add_f32_dpp v150, v150, v150 row_half_mirror row_mask:0xf bank_mask:0xf bound_ctrl:1
	v_add_f32_dpp v151, v151, v151 row_half_mirror row_mask:0xf bank_mask:0xf bound_ctrl:1
	v_pk_fma_f32 v[106:107], v[144:145], v[142:143], v[106:107] op_sel:[0,1,0]
	v_add_f32_dpp v148, v148, v148 row_mirror row_mask:0xf bank_mask:0xf bound_ctrl:1
	v_add_f32_dpp v149, v149, v149 row_mirror row_mask:0xf bank_mask:0xf bound_ctrl:1
	v_add_f32_dpp v150, v150, v150 row_mirror row_mask:0xf bank_mask:0xf bound_ctrl:1
	v_pk_fma_f32 v[100:101], v[148:149], v[136:137], v[100:101] op_sel_hi:[1,0,1]
	v_pk_fma_f32 v[102:103], v[148:149], v[136:137], v[102:103] op_sel:[0,1,0]
	v_pk_fma_f32 v[104:105], v[148:149], v[138:139], v[104:105] op_sel_hi:[1,0,1]
	v_pk_fma_f32 v[106:107], v[148:149], v[138:139], v[106:107] op_sel:[0,1,0]
	v_add_f32_dpp v151, v151, v151 row_mirror row_mask:0xf bank_mask:0xf bound_ctrl:1
	v_pk_fma_f32 v[152:153], v[148:149], v[146:147], v[150:151] op_sel_hi:[1,0,1]
	v_pk_fma_f32 v[152:153], v[144:145], v[146:147], v[152:153] op_sel:[0,1,0]
	v_cvt_pk_bf16_f32 v154, v152, v153
	s_waitcnt lgkmcnt(0)
	ds_read_b128 v[128:131], v156 offset:17072
	ds_read_b128 v[132:135], v156 offset:17328
	ds_read_b128 v[140:143], v156 offset:18096
	ds_read_b64 v[144:145], v157 offset:17072
	ds_read_b128 v[136:139], v156 offset:17840
	ds_read_b64 v[146:147], v158 offset:17072
	v_mov_b32_dpp v155, v154 row_shr:9 row_mask:0xf bank_mask:0xf
	v_pk_mul_f32 v[148:149], v[100:101], v[108:109] op_sel_hi:[1,0]
	v_pk_mul_f32 v[150:151], v[100:101], v[112:113] op_sel_hi:[1,0]
	v_pk_fma_f32 v[148:149], v[102:103], v[108:109], v[148:149] op_sel:[0,1,0]
	v_pk_fma_f32 v[150:151], v[102:103], v[112:113], v[150:151] op_sel:[0,1,0]
	v_pk_fma_f32 v[148:149], v[104:105], v[110:111], v[148:149] op_sel_hi:[1,0,1]
	v_pk_fma_f32 v[150:151], v[104:105], v[114:115], v[150:151] op_sel_hi:[1,0,1]
	v_pk_fma_f32 v[148:149], v[106:107], v[110:111], v[148:149] op_sel:[0,1,0]
	v_pk_fma_f32 v[150:151], v[106:107], v[114:115], v[150:151] op_sel:[0,1,0]
	v_pk_fma_f32 v[100:101], v[124:125], v[120:121], v[100:101] op_sel_hi:[1,0,1]
	v_add_f32_dpp v148, v148, v148 quad_perm:[1,0,3,2] row_mask:0xf bank_mask:0xf bound_ctrl:1
	v_add_f32_dpp v149, v149, v149 quad_perm:[1,0,3,2] row_mask:0xf bank_mask:0xf bound_ctrl:1
	v_add_f32_dpp v150, v150, v150 quad_perm:[1,0,3,2] row_mask:0xf bank_mask:0xf bound_ctrl:1
	v_add_f32_dpp v151, v151, v151 quad_perm:[1,0,3,2] row_mask:0xf bank_mask:0xf bound_ctrl:1
	v_pk_fma_f32 v[102:103], v[124:125], v[120:121], v[102:103] op_sel:[0,1,0]
	v_add_f32_dpp v148, v148, v148 quad_perm:[2,3,0,1] row_mask:0xf bank_mask:0xf bound_ctrl:1
	v_add_f32_dpp v149, v149, v149 quad_perm:[2,3,0,1] row_mask:0xf bank_mask:0xf bound_ctrl:1
	v_add_f32_dpp v150, v150, v150 quad_perm:[2,3,0,1] row_mask:0xf bank_mask:0xf bound_ctrl:1
	v_add_f32_dpp v151, v151, v151 quad_perm:[2,3,0,1] row_mask:0xf bank_mask:0xf bound_ctrl:1
	v_pk_fma_f32 v[104:105], v[124:125], v[122:123], v[104:105] op_sel_hi:[1,0,1]
	v_add_f32_dpp v148, v148, v148 row_half_mirror row_mask:0xf bank_mask:0xf bound_ctrl:1
	v_add_f32_dpp v149, v149, v149 row_half_mirror row_mask:0xf bank_mask:0xf bound_ctrl:1
	v_add_f32_dpp v150, v150, v150 row_half_mirror row_mask:0xf bank_mask:0xf bound_ctrl:1
	v_add_f32_dpp v151, v151, v151 row_half_mirror row_mask:0xf bank_mask:0xf bound_ctrl:1
	v_pk_fma_f32 v[106:107], v[124:125], v[122:123], v[106:107] op_sel:[0,1,0]
	v_add_f32_dpp v148, v148, v148 row_mirror row_mask:0xf bank_mask:0xf bound_ctrl:1
	v_add_f32_dpp v149, v149, v149 row_mirror row_mask:0xf bank_mask:0xf bound_ctrl:1
	v_add_f32_dpp v150, v150, v150 row_mirror row_mask:0xf bank_mask:0xf bound_ctrl:1
	v_pk_fma_f32 v[100:101], v[148:149], v[116:117], v[100:101] op_sel_hi:[1,0,1]
	v_pk_fma_f32 v[102:103], v[148:149], v[116:117], v[102:103] op_sel:[0,1,0]
	v_pk_fma_f32 v[104:105], v[148:149], v[118:119], v[104:105] op_sel_hi:[1,0,1]
	v_pk_fma_f32 v[106:107], v[148:149], v[118:119], v[106:107] op_sel:[0,1,0]
	v_add_f32_dpp v151, v151, v151 row_mirror row_mask:0xf bank_mask:0xf bound_ctrl:1
	v_pk_fma_f32 v[152:153], v[148:149], v[126:127], v[150:151] op_sel_hi:[1,0,1]
	v_pk_fma_f32 v[152:153], v[124:125], v[126:127], v[152:153] op_sel:[0,1,0]
	v_cvt_pk_bf16_f32 v154, v152, v153
	s_waitcnt lgkmcnt(0)
	ds_read_b128 v[108:111], v156 offset:18624
	ds_read_b128 v[112:115], v156 offset:18880
	ds_read_b128 v[120:123], v156 offset:19648
	ds_read_b64 v[124:125], v157 offset:18624
	ds_read_b128 v[116:119], v156 offset:19392
	ds_read_b64 v[126:127], v158 offset:18624
	v_mov_b32_dpp v155, v154 row_shr:10 row_mask:0xf bank_mask:0xf
	v_pk_mul_f32 v[148:149], v[100:101], v[128:129] op_sel_hi:[1,0]
	v_pk_mul_f32 v[150:151], v[100:101], v[132:133] op_sel_hi:[1,0]
	v_pk_fma_f32 v[148:149], v[102:103], v[128:129], v[148:149] op_sel:[0,1,0]
	v_pk_fma_f32 v[150:151], v[102:103], v[132:133], v[150:151] op_sel:[0,1,0]
	v_pk_fma_f32 v[148:149], v[104:105], v[130:131], v[148:149] op_sel_hi:[1,0,1]
	v_pk_fma_f32 v[150:151], v[104:105], v[134:135], v[150:151] op_sel_hi:[1,0,1]
	v_pk_fma_f32 v[148:149], v[106:107], v[130:131], v[148:149] op_sel:[0,1,0]
	v_pk_fma_f32 v[150:151], v[106:107], v[134:135], v[150:151] op_sel:[0,1,0]
	v_pk_fma_f32 v[100:101], v[144:145], v[140:141], v[100:101] op_sel_hi:[1,0,1]
	v_add_f32_dpp v148, v148, v148 quad_perm:[1,0,3,2] row_mask:0xf bank_mask:0xf bound_ctrl:1
	v_add_f32_dpp v149, v149, v149 quad_perm:[1,0,3,2] row_mask:0xf bank_mask:0xf bound_ctrl:1
	v_add_f32_dpp v150, v150, v150 quad_perm:[1,0,3,2] row_mask:0xf bank_mask:0xf bound_ctrl:1
	v_add_f32_dpp v151, v151, v151 quad_perm:[1,0,3,2] row_mask:0xf bank_mask:0xf bound_ctrl:1
	v_pk_fma_f32 v[102:103], v[144:145], v[140:141], v[102:103] op_sel:[0,1,0]
	v_add_f32_dpp v148, v148, v148 quad_perm:[2,3,0,1] row_mask:0xf bank_mask:0xf bound_ctrl:1
	v_add_f32_dpp v149, v149, v149 quad_perm:[2,3,0,1] row_mask:0xf bank_mask:0xf bound_ctrl:1
	v_add_f32_dpp v150, v150, v150 quad_perm:[2,3,0,1] row_mask:0xf bank_mask:0xf bound_ctrl:1
	v_add_f32_dpp v151, v151, v151 quad_perm:[2,3,0,1] row_mask:0xf bank_mask:0xf bound_ctrl:1
	v_pk_fma_f32 v[104:105], v[144:145], v[142:143], v[104:105] op_sel_hi:[1,0,1]
	v_add_f32_dpp v148, v148, v148 row_half_mirror row_mask:0xf bank_mask:0xf bound_ctrl:1
	v_add_f32_dpp v149, v149, v149 row_half_mirror row_mask:0xf bank_mask:0xf bound_ctrl:1
	v_add_f32_dpp v150, v150, v150 row_half_mirror row_mask:0xf bank_mask:0xf bound_ctrl:1
	v_add_f32_dpp v151, v151, v151 row_half_mirror row_mask:0xf bank_mask:0xf bound_ctrl:1
	v_pk_fma_f32 v[106:107], v[144:145], v[142:143], v[106:107] op_sel:[0,1,0]
	v_add_f32_dpp v148, v148, v148 row_mirror row_mask:0xf bank_mask:0xf bound_ctrl:1
	v_add_f32_dpp v149, v149, v149 row_mirror row_mask:0xf bank_mask:0xf bound_ctrl:1
	v_add_f32_dpp v150, v150, v150 row_mirror row_mask:0xf bank_mask:0xf bound_ctrl:1
	v_pk_fma_f32 v[100:101], v[148:149], v[136:137], v[100:101] op_sel_hi:[1,0,1]
	v_pk_fma_f32 v[102:103], v[148:149], v[136:137], v[102:103] op_sel:[0,1,0]
	v_pk_fma_f32 v[104:105], v[148:149], v[138:139], v[104:105] op_sel_hi:[1,0,1]
	v_pk_fma_f32 v[106:107], v[148:149], v[138:139], v[106:107] op_sel:[0,1,0]
	v_add_f32_dpp v151, v151, v151 row_mirror row_mask:0xf bank_mask:0xf bound_ctrl:1
	v_pk_fma_f32 v[152:153], v[148:149], v[146:147], v[150:151] op_sel_hi:[1,0,1]
	v_pk_fma_f32 v[152:153], v[144:145], v[146:147], v[152:153] op_sel:[0,1,0]
	v_cvt_pk_bf16_f32 v154, v152, v153
	s_waitcnt lgkmcnt(0)
	ds_read_b128 v[128:131], v156 offset:20176
	ds_read_b128 v[132:135], v156 offset:20432
	ds_read_b128 v[140:143], v156 offset:21200
	ds_read_b64 v[144:145], v157 offset:20176
	ds_read_b128 v[136:139], v156 offset:20944
	ds_read_b64 v[146:147], v158 offset:20176
	v_mov_b32_dpp v155, v154 row_shr:11 row_mask:0xf bank_mask:0xf
	v_pk_mul_f32 v[148:149], v[100:101], v[108:109] op_sel_hi:[1,0]
	v_pk_mul_f32 v[150:151], v[100:101], v[112:113] op_sel_hi:[1,0]
	v_pk_fma_f32 v[148:149], v[102:103], v[108:109], v[148:149] op_sel:[0,1,0]
	v_pk_fma_f32 v[150:151], v[102:103], v[112:113], v[150:151] op_sel:[0,1,0]
	v_pk_fma_f32 v[148:149], v[104:105], v[110:111], v[148:149] op_sel_hi:[1,0,1]
	v_pk_fma_f32 v[150:151], v[104:105], v[114:115], v[150:151] op_sel_hi:[1,0,1]
	v_pk_fma_f32 v[148:149], v[106:107], v[110:111], v[148:149] op_sel:[0,1,0]
	v_pk_fma_f32 v[150:151], v[106:107], v[114:115], v[150:151] op_sel:[0,1,0]
	v_pk_fma_f32 v[100:101], v[124:125], v[120:121], v[100:101] op_sel_hi:[1,0,1]
	v_add_f32_dpp v148, v148, v148 quad_perm:[1,0,3,2] row_mask:0xf bank_mask:0xf bound_ctrl:1
	v_add_f32_dpp v149, v149, v149 quad_perm:[1,0,3,2] row_mask:0xf bank_mask:0xf bound_ctrl:1
	v_add_f32_dpp v150, v150, v150 quad_perm:[1,0,3,2] row_mask:0xf bank_mask:0xf bound_ctrl:1
	v_add_f32_dpp v151, v151, v151 quad_perm:[1,0,3,2] row_mask:0xf bank_mask:0xf bound_ctrl:1
	v_pk_fma_f32 v[102:103], v[124:125], v[120:121], v[102:103] op_sel:[0,1,0]
	v_add_f32_dpp v148, v148, v148 quad_perm:[2,3,0,1] row_mask:0xf bank_mask:0xf bound_ctrl:1
	v_add_f32_dpp v149, v149, v149 quad_perm:[2,3,0,1] row_mask:0xf bank_mask:0xf bound_ctrl:1
	v_add_f32_dpp v150, v150, v150 quad_perm:[2,3,0,1] row_mask:0xf bank_mask:0xf bound_ctrl:1
	v_add_f32_dpp v151, v151, v151 quad_perm:[2,3,0,1] row_mask:0xf bank_mask:0xf bound_ctrl:1
	v_pk_fma_f32 v[104:105], v[124:125], v[122:123], v[104:105] op_sel_hi:[1,0,1]
	v_add_f32_dpp v148, v148, v148 row_half_mirror row_mask:0xf bank_mask:0xf bound_ctrl:1
	v_add_f32_dpp v149, v149, v149 row_half_mirror row_mask:0xf bank_mask:0xf bound_ctrl:1
	v_add_f32_dpp v150, v150, v150 row_half_mirror row_mask:0xf bank_mask:0xf bound_ctrl:1
	v_add_f32_dpp v151, v151, v151 row_half_mirror row_mask:0xf bank_mask:0xf bound_ctrl:1
	v_pk_fma_f32 v[106:107], v[124:125], v[122:123], v[106:107] op_sel:[0,1,0]
	v_add_f32_dpp v148, v148, v148 row_mirror row_mask:0xf bank_mask:0xf bound_ctrl:1
	v_add_f32_dpp v149, v149, v149 row_mirror row_mask:0xf bank_mask:0xf bound_ctrl:1
	v_add_f32_dpp v150, v150, v150 row_mirror row_mask:0xf bank_mask:0xf bound_ctrl:1
	v_pk_fma_f32 v[100:101], v[148:149], v[116:117], v[100:101] op_sel_hi:[1,0,1]
	v_pk_fma_f32 v[102:103], v[148:149], v[116:117], v[102:103] op_sel:[0,1,0]
	v_pk_fma_f32 v[104:105], v[148:149], v[118:119], v[104:105] op_sel_hi:[1,0,1]
	v_pk_fma_f32 v[106:107], v[148:149], v[118:119], v[106:107] op_sel:[0,1,0]
	v_add_f32_dpp v151, v151, v151 row_mirror row_mask:0xf bank_mask:0xf bound_ctrl:1
	v_pk_fma_f32 v[152:153], v[148:149], v[126:127], v[150:151] op_sel_hi:[1,0,1]
	v_pk_fma_f32 v[152:153], v[124:125], v[126:127], v[152:153] op_sel:[0,1,0]
	v_cvt_pk_bf16_f32 v154, v152, v153
	s_waitcnt lgkmcnt(0)
	ds_read_b128 v[108:111], v156 offset:21728
	ds_read_b128 v[112:115], v156 offset:21984
	ds_read_b128 v[120:123], v156 offset:22752
	ds_read_b64 v[124:125], v157 offset:21728
	ds_read_b128 v[116:119], v156 offset:22496
	ds_read_b64 v[126:127], v158 offset:21728
	v_mov_b32_dpp v155, v154 row_shr:12 row_mask:0xf bank_mask:0xf
	v_pk_mul_f32 v[148:149], v[100:101], v[128:129] op_sel_hi:[1,0]
	v_pk_mul_f32 v[150:151], v[100:101], v[132:133] op_sel_hi:[1,0]
	v_pk_fma_f32 v[148:149], v[102:103], v[128:129], v[148:149] op_sel:[0,1,0]
	v_pk_fma_f32 v[150:151], v[102:103], v[132:133], v[150:151] op_sel:[0,1,0]
	v_pk_fma_f32 v[148:149], v[104:105], v[130:131], v[148:149] op_sel_hi:[1,0,1]
	v_pk_fma_f32 v[150:151], v[104:105], v[134:135], v[150:151] op_sel_hi:[1,0,1]
	v_pk_fma_f32 v[148:149], v[106:107], v[130:131], v[148:149] op_sel:[0,1,0]
	v_pk_fma_f32 v[150:151], v[106:107], v[134:135], v[150:151] op_sel:[0,1,0]
	v_pk_fma_f32 v[100:101], v[144:145], v[140:141], v[100:101] op_sel_hi:[1,0,1]
	v_add_f32_dpp v148, v148, v148 quad_perm:[1,0,3,2] row_mask:0xf bank_mask:0xf bound_ctrl:1
	v_add_f32_dpp v149, v149, v149 quad_perm:[1,0,3,2] row_mask:0xf bank_mask:0xf bound_ctrl:1
	v_add_f32_dpp v150, v150, v150 quad_perm:[1,0,3,2] row_mask:0xf bank_mask:0xf bound_ctrl:1
	v_add_f32_dpp v151, v151, v151 quad_perm:[1,0,3,2] row_mask:0xf bank_mask:0xf bound_ctrl:1
	v_pk_fma_f32 v[102:103], v[144:145], v[140:141], v[102:103] op_sel:[0,1,0]
	v_add_f32_dpp v148, v148, v148 quad_perm:[2,3,0,1] row_mask:0xf bank_mask:0xf bound_ctrl:1
	v_add_f32_dpp v149, v149, v149 quad_perm:[2,3,0,1] row_mask:0xf bank_mask:0xf bound_ctrl:1
	v_add_f32_dpp v150, v150, v150 quad_perm:[2,3,0,1] row_mask:0xf bank_mask:0xf bound_ctrl:1
	v_add_f32_dpp v151, v151, v151 quad_perm:[2,3,0,1] row_mask:0xf bank_mask:0xf bound_ctrl:1
	v_pk_fma_f32 v[104:105], v[144:145], v[142:143], v[104:105] op_sel_hi:[1,0,1]
	v_add_f32_dpp v148, v148, v148 row_half_mirror row_mask:0xf bank_mask:0xf bound_ctrl:1
	v_add_f32_dpp v149, v149, v149 row_half_mirror row_mask:0xf bank_mask:0xf bound_ctrl:1
	v_add_f32_dpp v150, v150, v150 row_half_mirror row_mask:0xf bank_mask:0xf bound_ctrl:1
	v_add_f32_dpp v151, v151, v151 row_half_mirror row_mask:0xf bank_mask:0xf bound_ctrl:1
	v_pk_fma_f32 v[106:107], v[144:145], v[142:143], v[106:107] op_sel:[0,1,0]
	v_add_f32_dpp v148, v148, v148 row_mirror row_mask:0xf bank_mask:0xf bound_ctrl:1
	v_add_f32_dpp v149, v149, v149 row_mirror row_mask:0xf bank_mask:0xf bound_ctrl:1
	v_add_f32_dpp v150, v150, v150 row_mirror row_mask:0xf bank_mask:0xf bound_ctrl:1
	v_pk_fma_f32 v[100:101], v[148:149], v[136:137], v[100:101] op_sel_hi:[1,0,1]
	v_pk_fma_f32 v[102:103], v[148:149], v[136:137], v[102:103] op_sel:[0,1,0]
	v_pk_fma_f32 v[104:105], v[148:149], v[138:139], v[104:105] op_sel_hi:[1,0,1]
	v_pk_fma_f32 v[106:107], v[148:149], v[138:139], v[106:107] op_sel:[0,1,0]
	v_add_f32_dpp v151, v151, v151 row_mirror row_mask:0xf bank_mask:0xf bound_ctrl:1
	v_pk_fma_f32 v[152:153], v[148:149], v[146:147], v[150:151] op_sel_hi:[1,0,1]
	v_pk_fma_f32 v[152:153], v[144:145], v[146:147], v[152:153] op_sel:[0,1,0]
	v_cvt_pk_bf16_f32 v154, v152, v153
	s_waitcnt lgkmcnt(0)
	ds_read_b128 v[128:131], v156 offset:23280
	ds_read_b128 v[132:135], v156 offset:23536
	ds_read_b128 v[140:143], v156 offset:24304
	ds_read_b64 v[144:145], v157 offset:23280
	ds_read_b128 v[136:139], v156 offset:24048
	ds_read_b64 v[146:147], v158 offset:23280
	v_mov_b32_dpp v155, v154 row_shr:13 row_mask:0xf bank_mask:0xf
	v_pk_mul_f32 v[148:149], v[100:101], v[108:109] op_sel_hi:[1,0]
	v_pk_mul_f32 v[150:151], v[100:101], v[112:113] op_sel_hi:[1,0]
	v_pk_fma_f32 v[148:149], v[102:103], v[108:109], v[148:149] op_sel:[0,1,0]
	v_pk_fma_f32 v[150:151], v[102:103], v[112:113], v[150:151] op_sel:[0,1,0]
	v_pk_fma_f32 v[148:149], v[104:105], v[110:111], v[148:149] op_sel_hi:[1,0,1]
	v_pk_fma_f32 v[150:151], v[104:105], v[114:115], v[150:151] op_sel_hi:[1,0,1]
	v_pk_fma_f32 v[148:149], v[106:107], v[110:111], v[148:149] op_sel:[0,1,0]
	v_pk_fma_f32 v[150:151], v[106:107], v[114:115], v[150:151] op_sel:[0,1,0]
	v_pk_fma_f32 v[100:101], v[124:125], v[120:121], v[100:101] op_sel_hi:[1,0,1]
	v_add_f32_dpp v148, v148, v148 quad_perm:[1,0,3,2] row_mask:0xf bank_mask:0xf bound_ctrl:1
	v_add_f32_dpp v149, v149, v149 quad_perm:[1,0,3,2] row_mask:0xf bank_mask:0xf bound_ctrl:1
	v_add_f32_dpp v150, v150, v150 quad_perm:[1,0,3,2] row_mask:0xf bank_mask:0xf bound_ctrl:1
	v_add_f32_dpp v151, v151, v151 quad_perm:[1,0,3,2] row_mask:0xf bank_mask:0xf bound_ctrl:1
	v_pk_fma_f32 v[102:103], v[124:125], v[120:121], v[102:103] op_sel:[0,1,0]
	v_add_f32_dpp v148, v148, v148 quad_perm:[2,3,0,1] row_mask:0xf bank_mask:0xf bound_ctrl:1
	v_add_f32_dpp v149, v149, v149 quad_perm:[2,3,0,1] row_mask:0xf bank_mask:0xf bound_ctrl:1
	v_add_f32_dpp v150, v150, v150 quad_perm:[2,3,0,1] row_mask:0xf bank_mask:0xf bound_ctrl:1
	v_add_f32_dpp v151, v151, v151 quad_perm:[2,3,0,1] row_mask:0xf bank_mask:0xf bound_ctrl:1
	v_pk_fma_f32 v[104:105], v[124:125], v[122:123], v[104:105] op_sel_hi:[1,0,1]
	v_add_f32_dpp v148, v148, v148 row_half_mirror row_mask:0xf bank_mask:0xf bound_ctrl:1
	v_add_f32_dpp v149, v149, v149 row_half_mirror row_mask:0xf bank_mask:0xf bound_ctrl:1
	v_add_f32_dpp v150, v150, v150 row_half_mirror row_mask:0xf bank_mask:0xf bound_ctrl:1
	v_add_f32_dpp v151, v151, v151 row_half_mirror row_mask:0xf bank_mask:0xf bound_ctrl:1
	v_pk_fma_f32 v[106:107], v[124:125], v[122:123], v[106:107] op_sel:[0,1,0]
	v_add_f32_dpp v148, v148, v148 row_mirror row_mask:0xf bank_mask:0xf bound_ctrl:1
	v_add_f32_dpp v149, v149, v149 row_mirror row_mask:0xf bank_mask:0xf bound_ctrl:1
	v_add_f32_dpp v150, v150, v150 row_mirror row_mask:0xf bank_mask:0xf bound_ctrl:1
	v_pk_fma_f32 v[100:101], v[148:149], v[116:117], v[100:101] op_sel_hi:[1,0,1]
	v_pk_fma_f32 v[102:103], v[148:149], v[116:117], v[102:103] op_sel:[0,1,0]
	v_pk_fma_f32 v[104:105], v[148:149], v[118:119], v[104:105] op_sel_hi:[1,0,1]
	v_pk_fma_f32 v[106:107], v[148:149], v[118:119], v[106:107] op_sel:[0,1,0]
	v_add_f32_dpp v151, v151, v151 row_mirror row_mask:0xf bank_mask:0xf bound_ctrl:1
	v_pk_fma_f32 v[152:153], v[148:149], v[126:127], v[150:151] op_sel_hi:[1,0,1]
	v_pk_fma_f32 v[152:153], v[124:125], v[126:127], v[152:153] op_sel:[0,1,0]
	v_cvt_pk_bf16_f32 v154, v152, v153
	s_waitcnt lgkmcnt(0)
	ds_read_b128 v[108:111], v156 offset:24832
	ds_read_b128 v[112:115], v156 offset:25088
	ds_read_b128 v[120:123], v156 offset:25856
	ds_read_b64 v[124:125], v157 offset:24832
	ds_read_b128 v[116:119], v156 offset:25600
	ds_read_b64 v[126:127], v158 offset:24832
	v_mov_b32_dpp v155, v154 row_shr:14 row_mask:0xf bank_mask:0xf
	v_pk_mul_f32 v[148:149], v[100:101], v[128:129] op_sel_hi:[1,0]
	v_pk_mul_f32 v[150:151], v[100:101], v[132:133] op_sel_hi:[1,0]
	v_pk_fma_f32 v[148:149], v[102:103], v[128:129], v[148:149] op_sel:[0,1,0]
	v_pk_fma_f32 v[150:151], v[102:103], v[132:133], v[150:151] op_sel:[0,1,0]
	v_pk_fma_f32 v[148:149], v[104:105], v[130:131], v[148:149] op_sel_hi:[1,0,1]
	v_pk_fma_f32 v[150:151], v[104:105], v[134:135], v[150:151] op_sel_hi:[1,0,1]
	v_pk_fma_f32 v[148:149], v[106:107], v[130:131], v[148:149] op_sel:[0,1,0]
	v_pk_fma_f32 v[150:151], v[106:107], v[134:135], v[150:151] op_sel:[0,1,0]
	v_pk_fma_f32 v[100:101], v[144:145], v[140:141], v[100:101] op_sel_hi:[1,0,1]
	v_add_f32_dpp v148, v148, v148 quad_perm:[1,0,3,2] row_mask:0xf bank_mask:0xf bound_ctrl:1
	v_add_f32_dpp v149, v149, v149 quad_perm:[1,0,3,2] row_mask:0xf bank_mask:0xf bound_ctrl:1
	v_add_f32_dpp v150, v150, v150 quad_perm:[1,0,3,2] row_mask:0xf bank_mask:0xf bound_ctrl:1
	v_add_f32_dpp v151, v151, v151 quad_perm:[1,0,3,2] row_mask:0xf bank_mask:0xf bound_ctrl:1
	v_pk_fma_f32 v[102:103], v[144:145], v[140:141], v[102:103] op_sel:[0,1,0]
	v_add_f32_dpp v148, v148, v148 quad_perm:[2,3,0,1] row_mask:0xf bank_mask:0xf bound_ctrl:1
	v_add_f32_dpp v149, v149, v149 quad_perm:[2,3,0,1] row_mask:0xf bank_mask:0xf bound_ctrl:1
	v_add_f32_dpp v150, v150, v150 quad_perm:[2,3,0,1] row_mask:0xf bank_mask:0xf bound_ctrl:1
	v_add_f32_dpp v151, v151, v151 quad_perm:[2,3,0,1] row_mask:0xf bank_mask:0xf bound_ctrl:1
	v_pk_fma_f32 v[104:105], v[144:145], v[142:143], v[104:105] op_sel_hi:[1,0,1]
	v_add_f32_dpp v148, v148, v148 row_half_mirror row_mask:0xf bank_mask:0xf bound_ctrl:1
	v_add_f32_dpp v149, v149, v149 row_half_mirror row_mask:0xf bank_mask:0xf bound_ctrl:1
	v_add_f32_dpp v150, v150, v150 row_half_mirror row_mask:0xf bank_mask:0xf bound_ctrl:1
	v_add_f32_dpp v151, v151, v151 row_half_mirror row_mask:0xf bank_mask:0xf bound_ctrl:1
	v_pk_fma_f32 v[106:107], v[144:145], v[142:143], v[106:107] op_sel:[0,1,0]
	v_add_f32_dpp v148, v148, v148 row_mirror row_mask:0xf bank_mask:0xf bound_ctrl:1
	v_add_f32_dpp v149, v149, v149 row_mirror row_mask:0xf bank_mask:0xf bound_ctrl:1
	v_add_f32_dpp v150, v150, v150 row_mirror row_mask:0xf bank_mask:0xf bound_ctrl:1
	v_pk_fma_f32 v[100:101], v[148:149], v[136:137], v[100:101] op_sel_hi:[1,0,1]
	v_pk_fma_f32 v[102:103], v[148:149], v[136:137], v[102:103] op_sel:[0,1,0]
	v_pk_fma_f32 v[104:105], v[148:149], v[138:139], v[104:105] op_sel_hi:[1,0,1]
	v_pk_fma_f32 v[106:107], v[148:149], v[138:139], v[106:107] op_sel:[0,1,0]
	v_add_f32_dpp v151, v151, v151 row_mirror row_mask:0xf bank_mask:0xf bound_ctrl:1
	v_pk_fma_f32 v[152:153], v[148:149], v[146:147], v[150:151] op_sel_hi:[1,0,1]
	v_pk_fma_f32 v[152:153], v[144:145], v[146:147], v[152:153] op_sel:[0,1,0]
	v_cvt_pk_bf16_f32 v154, v152, v153
	s_waitcnt lgkmcnt(0)
	ds_read_b128 v[128:131], v156 offset:26384
	ds_read_b128 v[132:135], v156 offset:26640
	ds_read_b128 v[140:143], v156 offset:27408
	ds_read_b64 v[144:145], v157 offset:26384
	ds_read_b128 v[136:139], v156 offset:27152
	ds_read_b64 v[146:147], v158 offset:26384
	v_mov_b32_dpp v155, v154 row_shr:15 row_mask:0xf bank_mask:0xf
	global_store_dword v[160:161], v155, off
	v_lshl_add_u64 v[160:161], v[160:161], 0, s[100:101]
	v_pk_mul_f32 v[148:149], v[100:101], v[108:109] op_sel_hi:[1,0]
	v_pk_mul_f32 v[150:151], v[100:101], v[112:113] op_sel_hi:[1,0]
	v_pk_fma_f32 v[148:149], v[102:103], v[108:109], v[148:149] op_sel:[0,1,0]
	v_pk_fma_f32 v[150:151], v[102:103], v[112:113], v[150:151] op_sel:[0,1,0]
	v_pk_fma_f32 v[148:149], v[104:105], v[110:111], v[148:149] op_sel_hi:[1,0,1]
	v_pk_fma_f32 v[150:151], v[104:105], v[114:115], v[150:151] op_sel_hi:[1,0,1]
	v_pk_fma_f32 v[148:149], v[106:107], v[110:111], v[148:149] op_sel:[0,1,0]
	v_pk_fma_f32 v[150:151], v[106:107], v[114:115], v[150:151] op_sel:[0,1,0]
	v_pk_fma_f32 v[100:101], v[124:125], v[120:121], v[100:101] op_sel_hi:[1,0,1]
	v_add_f32_dpp v148, v148, v148 quad_perm:[1,0,3,2] row_mask:0xf bank_mask:0xf bound_ctrl:1
	v_add_f32_dpp v149, v149, v149 quad_perm:[1,0,3,2] row_mask:0xf bank_mask:0xf bound_ctrl:1
	v_add_f32_dpp v150, v150, v150 quad_perm:[1,0,3,2] row_mask:0xf bank_mask:0xf bound_ctrl:1
	v_add_f32_dpp v151, v151, v151 quad_perm:[1,0,3,2] row_mask:0xf bank_mask:0xf bound_ctrl:1
	v_pk_fma_f32 v[102:103], v[124:125], v[120:121], v[102:103] op_sel:[0,1,0]
	v_add_f32_dpp v148, v148, v148 quad_perm:[2,3,0,1] row_mask:0xf bank_mask:0xf bound_ctrl:1
	v_add_f32_dpp v149, v149, v149 quad_perm:[2,3,0,1] row_mask:0xf bank_mask:0xf bound_ctrl:1
	v_add_f32_dpp v150, v150, v150 quad_perm:[2,3,0,1] row_mask:0xf bank_mask:0xf bound_ctrl:1
	v_add_f32_dpp v151, v151, v151 quad_perm:[2,3,0,1] row_mask:0xf bank_mask:0xf bound_ctrl:1
	v_pk_fma_f32 v[104:105], v[124:125], v[122:123], v[104:105] op_sel_hi:[1,0,1]
	v_add_f32_dpp v148, v148, v148 row_half_mirror row_mask:0xf bank_mask:0xf bound_ctrl:1
	v_add_f32_dpp v149, v149, v149 row_half_mirror row_mask:0xf bank_mask:0xf bound_ctrl:1
	v_add_f32_dpp v150, v150, v150 row_half_mirror row_mask:0xf bank_mask:0xf bound_ctrl:1
	v_add_f32_dpp v151, v151, v151 row_half_mirror row_mask:0xf bank_mask:0xf bound_ctrl:1
	v_pk_fma_f32 v[106:107], v[124:125], v[122:123], v[106:107] op_sel:[0,1,0]
	v_add_f32_dpp v148, v148, v148 row_mirror row_mask:0xf bank_mask:0xf bound_ctrl:1
	v_add_f32_dpp v149, v149, v149 row_mirror row_mask:0xf bank_mask:0xf bound_ctrl:1
	v_add_f32_dpp v150, v150, v150 row_mirror row_mask:0xf bank_mask:0xf bound_ctrl:1
	v_pk_fma_f32 v[100:101], v[148:149], v[116:117], v[100:101] op_sel_hi:[1,0,1]
	v_pk_fma_f32 v[102:103], v[148:149], v[116:117], v[102:103] op_sel:[0,1,0]
	v_pk_fma_f32 v[104:105], v[148:149], v[118:119], v[104:105] op_sel_hi:[1,0,1]
	v_pk_fma_f32 v[106:107], v[148:149], v[118:119], v[106:107] op_sel:[0,1,0]
	v_add_f32_dpp v151, v151, v151 row_mirror row_mask:0xf bank_mask:0xf bound_ctrl:1
	v_pk_fma_f32 v[152:153], v[148:149], v[126:127], v[150:151] op_sel_hi:[1,0,1]
	v_pk_fma_f32 v[152:153], v[124:125], v[126:127], v[152:153] op_sel:[0,1,0]
	v_cvt_pk_bf16_f32 v154, v152, v153
	s_waitcnt lgkmcnt(0)
	ds_read_b128 v[108:111], v156 offset:27936
	ds_read_b128 v[112:115], v156 offset:28192
	ds_read_b128 v[120:123], v156 offset:28960
	ds_read_b64 v[124:125], v157 offset:27936
	ds_read_b128 v[116:119], v156 offset:28704
	ds_read_b64 v[126:127], v158 offset:27936
	v_mov_b32_e32 v155, v154
	v_pk_mul_f32 v[148:149], v[100:101], v[128:129] op_sel_hi:[1,0]
	v_pk_mul_f32 v[150:151], v[100:101], v[132:133] op_sel_hi:[1,0]
	v_pk_fma_f32 v[148:149], v[102:103], v[128:129], v[148:149] op_sel:[0,1,0]
	v_pk_fma_f32 v[150:151], v[102:103], v[132:133], v[150:151] op_sel:[0,1,0]
	v_pk_fma_f32 v[148:149], v[104:105], v[130:131], v[148:149] op_sel_hi:[1,0,1]
	v_pk_fma_f32 v[150:151], v[104:105], v[134:135], v[150:151] op_sel_hi:[1,0,1]
	v_pk_fma_f32 v[148:149], v[106:107], v[130:131], v[148:149] op_sel:[0,1,0]
	v_pk_fma_f32 v[150:151], v[106:107], v[134:135], v[150:151] op_sel:[0,1,0]
	v_pk_fma_f32 v[100:101], v[144:145], v[140:141], v[100:101] op_sel_hi:[1,0,1]
	v_add_f32_dpp v148, v148, v148 quad_perm:[1,0,3,2] row_mask:0xf bank_mask:0xf bound_ctrl:1
	v_add_f32_dpp v149, v149, v149 quad_perm:[1,0,3,2] row_mask:0xf bank_mask:0xf bound_ctrl:1
	v_add_f32_dpp v150, v150, v150 quad_perm:[1,0,3,2] row_mask:0xf bank_mask:0xf bound_ctrl:1
	v_add_f32_dpp v151, v151, v151 quad_perm:[1,0,3,2] row_mask:0xf bank_mask:0xf bound_ctrl:1
	v_pk_fma_f32 v[102:103], v[144:145], v[140:141], v[102:103] op_sel:[0,1,0]
	v_add_f32_dpp v148, v148, v148 quad_perm:[2,3,0,1] row_mask:0xf bank_mask:0xf bound_ctrl:1
	v_add_f32_dpp v149, v149, v149 quad_perm:[2,3,0,1] row_mask:0xf bank_mask:0xf bound_ctrl:1
	v_add_f32_dpp v150, v150, v150 quad_perm:[2,3,0,1] row_mask:0xf bank_mask:0xf bound_ctrl:1
	v_add_f32_dpp v151, v151, v151 quad_perm:[2,3,0,1] row_mask:0xf bank_mask:0xf bound_ctrl:1
	v_pk_fma_f32 v[104:105], v[144:145], v[142:143], v[104:105] op_sel_hi:[1,0,1]
	v_add_f32_dpp v148, v148, v148 row_half_mirror row_mask:0xf bank_mask:0xf bound_ctrl:1
	v_add_f32_dpp v149, v149, v149 row_half_mirror row_mask:0xf bank_mask:0xf bound_ctrl:1
	v_add_f32_dpp v150, v150, v150 row_half_mirror row_mask:0xf bank_mask:0xf bound_ctrl:1
	v_add_f32_dpp v151, v151, v151 row_half_mirror row_mask:0xf bank_mask:0xf bound_ctrl:1
	v_pk_fma_f32 v[106:107], v[144:145], v[142:143], v[106:107] op_sel:[0,1,0]
	v_add_f32_dpp v148, v148, v148 row_mirror row_mask:0xf bank_mask:0xf bound_ctrl:1
	v_add_f32_dpp v149, v149, v149 row_mirror row_mask:0xf bank_mask:0xf bound_ctrl:1
	v_add_f32_dpp v150, v150, v150 row_mirror row_mask:0xf bank_mask:0xf bound_ctrl:1
	v_pk_fma_f32 v[100:101], v[148:149], v[136:137], v[100:101] op_sel_hi:[1,0,1]
	v_pk_fma_f32 v[102:103], v[148:149], v[136:137], v[102:103] op_sel:[0,1,0]
	v_pk_fma_f32 v[104:105], v[148:149], v[138:139], v[104:105] op_sel_hi:[1,0,1]
	v_pk_fma_f32 v[106:107], v[148:149], v[138:139], v[106:107] op_sel:[0,1,0]
	v_add_f32_dpp v151, v151, v151 row_mirror row_mask:0xf bank_mask:0xf bound_ctrl:1
	v_pk_fma_f32 v[152:153], v[148:149], v[146:147], v[150:151] op_sel_hi:[1,0,1]
	v_pk_fma_f32 v[152:153], v[144:145], v[146:147], v[152:153] op_sel:[0,1,0]
	v_cvt_pk_bf16_f32 v154, v152, v153
	s_waitcnt lgkmcnt(0)
	ds_read_b128 v[128:131], v156 offset:29488
	ds_read_b128 v[132:135], v156 offset:29744
	ds_read_b128 v[140:143], v156 offset:30512
	ds_read_b64 v[144:145], v157 offset:29488
	ds_read_b128 v[136:139], v156 offset:30256
	ds_read_b64 v[146:147], v158 offset:29488
	v_mov_b32_dpp v155, v154 row_shr:1 row_mask:0xf bank_mask:0xf
	v_pk_mul_f32 v[148:149], v[100:101], v[108:109] op_sel_hi:[1,0]
	v_pk_mul_f32 v[150:151], v[100:101], v[112:113] op_sel_hi:[1,0]
	v_pk_fma_f32 v[148:149], v[102:103], v[108:109], v[148:149] op_sel:[0,1,0]
	v_pk_fma_f32 v[150:151], v[102:103], v[112:113], v[150:151] op_sel:[0,1,0]
	v_pk_fma_f32 v[148:149], v[104:105], v[110:111], v[148:149] op_sel_hi:[1,0,1]
	v_pk_fma_f32 v[150:151], v[104:105], v[114:115], v[150:151] op_sel_hi:[1,0,1]
	v_pk_fma_f32 v[148:149], v[106:107], v[110:111], v[148:149] op_sel:[0,1,0]
	v_pk_fma_f32 v[150:151], v[106:107], v[114:115], v[150:151] op_sel:[0,1,0]
	v_pk_fma_f32 v[100:101], v[124:125], v[120:121], v[100:101] op_sel_hi:[1,0,1]
	v_add_f32_dpp v148, v148, v148 quad_perm:[1,0,3,2] row_mask:0xf bank_mask:0xf bound_ctrl:1
	v_add_f32_dpp v149, v149, v149 quad_perm:[1,0,3,2] row_mask:0xf bank_mask:0xf bound_ctrl:1
	v_add_f32_dpp v150, v150, v150 quad_perm:[1,0,3,2] row_mask:0xf bank_mask:0xf bound_ctrl:1
	v_add_f32_dpp v151, v151, v151 quad_perm:[1,0,3,2] row_mask:0xf bank_mask:0xf bound_ctrl:1
	v_pk_fma_f32 v[102:103], v[124:125], v[120:121], v[102:103] op_sel:[0,1,0]
	v_add_f32_dpp v148, v148, v148 quad_perm:[2,3,0,1] row_mask:0xf bank_mask:0xf bound_ctrl:1
	v_add_f32_dpp v149, v149, v149 quad_perm:[2,3,0,1] row_mask:0xf bank_mask:0xf bound_ctrl:1
	v_add_f32_dpp v150, v150, v150 quad_perm:[2,3,0,1] row_mask:0xf bank_mask:0xf bound_ctrl:1
	v_add_f32_dpp v151, v151, v151 quad_perm:[2,3,0,1] row_mask:0xf bank_mask:0xf bound_ctrl:1
	v_pk_fma_f32 v[104:105], v[124:125], v[122:123], v[104:105] op_sel_hi:[1,0,1]
	v_add_f32_dpp v148, v148, v148 row_half_mirror row_mask:0xf bank_mask:0xf bound_ctrl:1
	v_add_f32_dpp v149, v149, v149 row_half_mirror row_mask:0xf bank_mask:0xf bound_ctrl:1
	v_add_f32_dpp v150, v150, v150 row_half_mirror row_mask:0xf bank_mask:0xf bound_ctrl:1
	v_add_f32_dpp v151, v151, v151 row_half_mirror row_mask:0xf bank_mask:0xf bound_ctrl:1
	v_pk_fma_f32 v[106:107], v[124:125], v[122:123], v[106:107] op_sel:[0,1,0]
	v_add_f32_dpp v148, v148, v148 row_mirror row_mask:0xf bank_mask:0xf bound_ctrl:1
	v_add_f32_dpp v149, v149, v149 row_mirror row_mask:0xf bank_mask:0xf bound_ctrl:1
	v_add_f32_dpp v150, v150, v150 row_mirror row_mask:0xf bank_mask:0xf bound_ctrl:1
	v_pk_fma_f32 v[100:101], v[148:149], v[116:117], v[100:101] op_sel_hi:[1,0,1]
	v_pk_fma_f32 v[102:103], v[148:149], v[116:117], v[102:103] op_sel:[0,1,0]
	v_pk_fma_f32 v[104:105], v[148:149], v[118:119], v[104:105] op_sel_hi:[1,0,1]
	v_pk_fma_f32 v[106:107], v[148:149], v[118:119], v[106:107] op_sel:[0,1,0]
	v_add_f32_dpp v151, v151, v151 row_mirror row_mask:0xf bank_mask:0xf bound_ctrl:1
	v_pk_fma_f32 v[152:153], v[148:149], v[126:127], v[150:151] op_sel_hi:[1,0,1]
	v_pk_fma_f32 v[152:153], v[124:125], v[126:127], v[152:153] op_sel:[0,1,0]
	v_cvt_pk_bf16_f32 v154, v152, v153
	s_waitcnt lgkmcnt(0)
	ds_read_b128 v[108:111], v156 offset:31040
	ds_read_b128 v[112:115], v156 offset:31296
	ds_read_b128 v[120:123], v156 offset:32064
	ds_read_b64 v[124:125], v157 offset:31040
	ds_read_b128 v[116:119], v156 offset:31808
	ds_read_b64 v[126:127], v158 offset:31040
	v_mov_b32_dpp v155, v154 row_shr:2 row_mask:0xf bank_mask:0xf
	v_pk_mul_f32 v[148:149], v[100:101], v[128:129] op_sel_hi:[1,0]
	v_pk_mul_f32 v[150:151], v[100:101], v[132:133] op_sel_hi:[1,0]
	v_pk_fma_f32 v[148:149], v[102:103], v[128:129], v[148:149] op_sel:[0,1,0]
	v_pk_fma_f32 v[150:151], v[102:103], v[132:133], v[150:151] op_sel:[0,1,0]
	v_pk_fma_f32 v[148:149], v[104:105], v[130:131], v[148:149] op_sel_hi:[1,0,1]
	v_pk_fma_f32 v[150:151], v[104:105], v[134:135], v[150:151] op_sel_hi:[1,0,1]
	v_pk_fma_f32 v[148:149], v[106:107], v[130:131], v[148:149] op_sel:[0,1,0]
	v_pk_fma_f32 v[150:151], v[106:107], v[134:135], v[150:151] op_sel:[0,1,0]
	v_pk_fma_f32 v[100:101], v[144:145], v[140:141], v[100:101] op_sel_hi:[1,0,1]
	v_add_f32_dpp v148, v148, v148 quad_perm:[1,0,3,2] row_mask:0xf bank_mask:0xf bound_ctrl:1
	v_add_f32_dpp v149, v149, v149 quad_perm:[1,0,3,2] row_mask:0xf bank_mask:0xf bound_ctrl:1
	v_add_f32_dpp v150, v150, v150 quad_perm:[1,0,3,2] row_mask:0xf bank_mask:0xf bound_ctrl:1
	v_add_f32_dpp v151, v151, v151 quad_perm:[1,0,3,2] row_mask:0xf bank_mask:0xf bound_ctrl:1
	v_pk_fma_f32 v[102:103], v[144:145], v[140:141], v[102:103] op_sel:[0,1,0]
	v_add_f32_dpp v148, v148, v148 quad_perm:[2,3,0,1] row_mask:0xf bank_mask:0xf bound_ctrl:1
	v_add_f32_dpp v149, v149, v149 quad_perm:[2,3,0,1] row_mask:0xf bank_mask:0xf bound_ctrl:1
	v_add_f32_dpp v150, v150, v150 quad_perm:[2,3,0,1] row_mask:0xf bank_mask:0xf bound_ctrl:1
	v_add_f32_dpp v151, v151, v151 quad_perm:[2,3,0,1] row_mask:0xf bank_mask:0xf bound_ctrl:1
	v_pk_fma_f32 v[104:105], v[144:145], v[142:143], v[104:105] op_sel_hi:[1,0,1]
	v_add_f32_dpp v148, v148, v148 row_half_mirror row_mask:0xf bank_mask:0xf bound_ctrl:1
	v_add_f32_dpp v149, v149, v149 row_half_mirror row_mask:0xf bank_mask:0xf bound_ctrl:1
	v_add_f32_dpp v150, v150, v150 row_half_mirror row_mask:0xf bank_mask:0xf bound_ctrl:1
	v_add_f32_dpp v151, v151, v151 row_half_mirror row_mask:0xf bank_mask:0xf bound_ctrl:1
	v_pk_fma_f32 v[106:107], v[144:145], v[142:143], v[106:107] op_sel:[0,1,0]
	v_add_f32_dpp v148, v148, v148 row_mirror row_mask:0xf bank_mask:0xf bound_ctrl:1
	v_add_f32_dpp v149, v149, v149 row_mirror row_mask:0xf bank_mask:0xf bound_ctrl:1
	v_add_f32_dpp v150, v150, v150 row_mirror row_mask:0xf bank_mask:0xf bound_ctrl:1
	v_pk_fma_f32 v[100:101], v[148:149], v[136:137], v[100:101] op_sel_hi:[1,0,1]
	v_pk_fma_f32 v[102:103], v[148:149], v[136:137], v[102:103] op_sel:[0,1,0]
	v_pk_fma_f32 v[104:105], v[148:149], v[138:139], v[104:105] op_sel_hi:[1,0,1]
	v_pk_fma_f32 v[106:107], v[148:149], v[138:139], v[106:107] op_sel:[0,1,0]
	v_add_f32_dpp v151, v151, v151 row_mirror row_mask:0xf bank_mask:0xf bound_ctrl:1
	v_pk_fma_f32 v[152:153], v[148:149], v[146:147], v[150:151] op_sel_hi:[1,0,1]
	v_pk_fma_f32 v[152:153], v[144:145], v[146:147], v[152:153] op_sel:[0,1,0]
	v_cvt_pk_bf16_f32 v154, v152, v153
	s_waitcnt lgkmcnt(0)
	ds_read_b128 v[128:131], v156 offset:32592
	ds_read_b128 v[132:135], v156 offset:32848
	ds_read_b128 v[140:143], v156 offset:33616
	ds_read_b64 v[144:145], v157 offset:32592
	ds_read_b128 v[136:139], v156 offset:33360
	ds_read_b64 v[146:147], v158 offset:32592
	v_mov_b32_dpp v155, v154 row_shr:3 row_mask:0xf bank_mask:0xf
	v_pk_mul_f32 v[148:149], v[100:101], v[108:109] op_sel_hi:[1,0]
	v_pk_mul_f32 v[150:151], v[100:101], v[112:113] op_sel_hi:[1,0]
	v_pk_fma_f32 v[148:149], v[102:103], v[108:109], v[148:149] op_sel:[0,1,0]
	v_pk_fma_f32 v[150:151], v[102:103], v[112:113], v[150:151] op_sel:[0,1,0]
	v_pk_fma_f32 v[148:149], v[104:105], v[110:111], v[148:149] op_sel_hi:[1,0,1]
	v_pk_fma_f32 v[150:151], v[104:105], v[114:115], v[150:151] op_sel_hi:[1,0,1]
	v_pk_fma_f32 v[148:149], v[106:107], v[110:111], v[148:149] op_sel:[0,1,0]
	v_pk_fma_f32 v[150:151], v[106:107], v[114:115], v[150:151] op_sel:[0,1,0]
	v_pk_fma_f32 v[100:101], v[124:125], v[120:121], v[100:101] op_sel_hi:[1,0,1]
	v_add_f32_dpp v148, v148, v148 quad_perm:[1,0,3,2] row_mask:0xf bank_mask:0xf bound_ctrl:1
	v_add_f32_dpp v149, v149, v149 quad_perm:[1,0,3,2] row_mask:0xf bank_mask:0xf bound_ctrl:1
	v_add_f32_dpp v150, v150, v150 quad_perm:[1,0,3,2] row_mask:0xf bank_mask:0xf bound_ctrl:1
	v_add_f32_dpp v151, v151, v151 quad_perm:[1,0,3,2] row_mask:0xf bank_mask:0xf bound_ctrl:1
	v_pk_fma_f32 v[102:103], v[124:125], v[120:121], v[102:103] op_sel:[0,1,0]
	v_add_f32_dpp v148, v148, v148 quad_perm:[2,3,0,1] row_mask:0xf bank_mask:0xf bound_ctrl:1
	v_add_f32_dpp v149, v149, v149 quad_perm:[2,3,0,1] row_mask:0xf bank_mask:0xf bound_ctrl:1
	v_add_f32_dpp v150, v150, v150 quad_perm:[2,3,0,1] row_mask:0xf bank_mask:0xf bound_ctrl:1
	v_add_f32_dpp v151, v151, v151 quad_perm:[2,3,0,1] row_mask:0xf bank_mask:0xf bound_ctrl:1
	v_pk_fma_f32 v[104:105], v[124:125], v[122:123], v[104:105] op_sel_hi:[1,0,1]
	v_add_f32_dpp v148, v148, v148 row_half_mirror row_mask:0xf bank_mask:0xf bound_ctrl:1
	v_add_f32_dpp v149, v149, v149 row_half_mirror row_mask:0xf bank_mask:0xf bound_ctrl:1
	v_add_f32_dpp v150, v150, v150 row_half_mirror row_mask:0xf bank_mask:0xf bound_ctrl:1
	v_add_f32_dpp v151, v151, v151 row_half_mirror row_mask:0xf bank_mask:0xf bound_ctrl:1
	v_pk_fma_f32 v[106:107], v[124:125], v[122:123], v[106:107] op_sel:[0,1,0]
	v_add_f32_dpp v148, v148, v148 row_mirror row_mask:0xf bank_mask:0xf bound_ctrl:1
	v_add_f32_dpp v149, v149, v149 row_mirror row_mask:0xf bank_mask:0xf bound_ctrl:1
	v_add_f32_dpp v150, v150, v150 row_mirror row_mask:0xf bank_mask:0xf bound_ctrl:1
	v_pk_fma_f32 v[100:101], v[148:149], v[116:117], v[100:101] op_sel_hi:[1,0,1]
	v_pk_fma_f32 v[102:103], v[148:149], v[116:117], v[102:103] op_sel:[0,1,0]
	v_pk_fma_f32 v[104:105], v[148:149], v[118:119], v[104:105] op_sel_hi:[1,0,1]
	v_pk_fma_f32 v[106:107], v[148:149], v[118:119], v[106:107] op_sel:[0,1,0]
	v_add_f32_dpp v151, v151, v151 row_mirror row_mask:0xf bank_mask:0xf bound_ctrl:1
	v_pk_fma_f32 v[152:153], v[148:149], v[126:127], v[150:151] op_sel_hi:[1,0,1]
	v_pk_fma_f32 v[152:153], v[124:125], v[126:127], v[152:153] op_sel:[0,1,0]
	v_cvt_pk_bf16_f32 v154, v152, v153
	s_waitcnt lgkmcnt(0)
	ds_read_b128 v[108:111], v156 offset:34144
	ds_read_b128 v[112:115], v156 offset:34400
	ds_read_b128 v[120:123], v156 offset:35168
	ds_read_b64 v[124:125], v157 offset:34144
	ds_read_b128 v[116:119], v156 offset:34912
	ds_read_b64 v[126:127], v158 offset:34144
	v_mov_b32_dpp v155, v154 row_shr:4 row_mask:0xf bank_mask:0xf
	v_pk_mul_f32 v[148:149], v[100:101], v[128:129] op_sel_hi:[1,0]
	v_pk_mul_f32 v[150:151], v[100:101], v[132:133] op_sel_hi:[1,0]
	v_pk_fma_f32 v[148:149], v[102:103], v[128:129], v[148:149] op_sel:[0,1,0]
	v_pk_fma_f32 v[150:151], v[102:103], v[132:133], v[150:151] op_sel:[0,1,0]
	v_pk_fma_f32 v[148:149], v[104:105], v[130:131], v[148:149] op_sel_hi:[1,0,1]
	v_pk_fma_f32 v[150:151], v[104:105], v[134:135], v[150:151] op_sel_hi:[1,0,1]
	v_pk_fma_f32 v[148:149], v[106:107], v[130:131], v[148:149] op_sel:[0,1,0]
	v_pk_fma_f32 v[150:151], v[106:107], v[134:135], v[150:151] op_sel:[0,1,0]
	v_pk_fma_f32 v[100:101], v[144:145], v[140:141], v[100:101] op_sel_hi:[1,0,1]
	v_add_f32_dpp v148, v148, v148 quad_perm:[1,0,3,2] row_mask:0xf bank_mask:0xf bound_ctrl:1
	v_add_f32_dpp v149, v149, v149 quad_perm:[1,0,3,2] row_mask:0xf bank_mask:0xf bound_ctrl:1
	v_add_f32_dpp v150, v150, v150 quad_perm:[1,0,3,2] row_mask:0xf bank_mask:0xf bound_ctrl:1
	v_add_f32_dpp v151, v151, v151 quad_perm:[1,0,3,2] row_mask:0xf bank_mask:0xf bound_ctrl:1
	v_pk_fma_f32 v[102:103], v[144:145], v[140:141], v[102:103] op_sel:[0,1,0]
	v_add_f32_dpp v148, v148, v148 quad_perm:[2,3,0,1] row_mask:0xf bank_mask:0xf bound_ctrl:1
	v_add_f32_dpp v149, v149, v149 quad_perm:[2,3,0,1] row_mask:0xf bank_mask:0xf bound_ctrl:1
	v_add_f32_dpp v150, v150, v150 quad_perm:[2,3,0,1] row_mask:0xf bank_mask:0xf bound_ctrl:1
	v_add_f32_dpp v151, v151, v151 quad_perm:[2,3,0,1] row_mask:0xf bank_mask:0xf bound_ctrl:1
	v_pk_fma_f32 v[104:105], v[144:145], v[142:143], v[104:105] op_sel_hi:[1,0,1]
	v_add_f32_dpp v148, v148, v148 row_half_mirror row_mask:0xf bank_mask:0xf bound_ctrl:1
	v_add_f32_dpp v149, v149, v149 row_half_mirror row_mask:0xf bank_mask:0xf bound_ctrl:1
	v_add_f32_dpp v150, v150, v150 row_half_mirror row_mask:0xf bank_mask:0xf bound_ctrl:1
	v_add_f32_dpp v151, v151, v151 row_half_mirror row_mask:0xf bank_mask:0xf bound_ctrl:1
	v_pk_fma_f32 v[106:107], v[144:145], v[142:143], v[106:107] op_sel:[0,1,0]
	v_add_f32_dpp v148, v148, v148 row_mirror row_mask:0xf bank_mask:0xf bound_ctrl:1
	v_add_f32_dpp v149, v149, v149 row_mirror row_mask:0xf bank_mask:0xf bound_ctrl:1
	v_add_f32_dpp v150, v150, v150 row_mirror row_mask:0xf bank_mask:0xf bound_ctrl:1
	v_pk_fma_f32 v[100:101], v[148:149], v[136:137], v[100:101] op_sel_hi:[1,0,1]
	v_pk_fma_f32 v[102:103], v[148:149], v[136:137], v[102:103] op_sel:[0,1,0]
	v_pk_fma_f32 v[104:105], v[148:149], v[138:139], v[104:105] op_sel_hi:[1,0,1]
	v_pk_fma_f32 v[106:107], v[148:149], v[138:139], v[106:107] op_sel:[0,1,0]
	v_add_f32_dpp v151, v151, v151 row_mirror row_mask:0xf bank_mask:0xf bound_ctrl:1
	v_pk_fma_f32 v[152:153], v[148:149], v[146:147], v[150:151] op_sel_hi:[1,0,1]
	v_pk_fma_f32 v[152:153], v[144:145], v[146:147], v[152:153] op_sel:[0,1,0]
	v_cvt_pk_bf16_f32 v154, v152, v153
	s_waitcnt lgkmcnt(0)
	ds_read_b128 v[128:131], v156 offset:35696
	ds_read_b128 v[132:135], v156 offset:35952
	ds_read_b128 v[140:143], v156 offset:36720
	ds_read_b64 v[144:145], v157 offset:35696
	ds_read_b128 v[136:139], v156 offset:36464
	ds_read_b64 v[146:147], v158 offset:35696
	v_mov_b32_dpp v155, v154 row_shr:5 row_mask:0xf bank_mask:0xf
	v_pk_mul_f32 v[148:149], v[100:101], v[108:109] op_sel_hi:[1,0]
	v_pk_mul_f32 v[150:151], v[100:101], v[112:113] op_sel_hi:[1,0]
	v_pk_fma_f32 v[148:149], v[102:103], v[108:109], v[148:149] op_sel:[0,1,0]
	v_pk_fma_f32 v[150:151], v[102:103], v[112:113], v[150:151] op_sel:[0,1,0]
	v_pk_fma_f32 v[148:149], v[104:105], v[110:111], v[148:149] op_sel_hi:[1,0,1]
	v_pk_fma_f32 v[150:151], v[104:105], v[114:115], v[150:151] op_sel_hi:[1,0,1]
	v_pk_fma_f32 v[148:149], v[106:107], v[110:111], v[148:149] op_sel:[0,1,0]
	v_pk_fma_f32 v[150:151], v[106:107], v[114:115], v[150:151] op_sel:[0,1,0]
	v_pk_fma_f32 v[100:101], v[124:125], v[120:121], v[100:101] op_sel_hi:[1,0,1]
	v_add_f32_dpp v148, v148, v148 quad_perm:[1,0,3,2] row_mask:0xf bank_mask:0xf bound_ctrl:1
	v_add_f32_dpp v149, v149, v149 quad_perm:[1,0,3,2] row_mask:0xf bank_mask:0xf bound_ctrl:1
	v_add_f32_dpp v150, v150, v150 quad_perm:[1,0,3,2] row_mask:0xf bank_mask:0xf bound_ctrl:1
	v_add_f32_dpp v151, v151, v151 quad_perm:[1,0,3,2] row_mask:0xf bank_mask:0xf bound_ctrl:1
	v_pk_fma_f32 v[102:103], v[124:125], v[120:121], v[102:103] op_sel:[0,1,0]
	v_add_f32_dpp v148, v148, v148 quad_perm:[2,3,0,1] row_mask:0xf bank_mask:0xf bound_ctrl:1
	v_add_f32_dpp v149, v149, v149 quad_perm:[2,3,0,1] row_mask:0xf bank_mask:0xf bound_ctrl:1
	v_add_f32_dpp v150, v150, v150 quad_perm:[2,3,0,1] row_mask:0xf bank_mask:0xf bound_ctrl:1
	v_add_f32_dpp v151, v151, v151 quad_perm:[2,3,0,1] row_mask:0xf bank_mask:0xf bound_ctrl:1
	v_pk_fma_f32 v[104:105], v[124:125], v[122:123], v[104:105] op_sel_hi:[1,0,1]
	v_add_f32_dpp v148, v148, v148 row_half_mirror row_mask:0xf bank_mask:0xf bound_ctrl:1
	v_add_f32_dpp v149, v149, v149 row_half_mirror row_mask:0xf bank_mask:0xf bound_ctrl:1
	v_add_f32_dpp v150, v150, v150 row_half_mirror row_mask:0xf bank_mask:0xf bound_ctrl:1
	v_add_f32_dpp v151, v151, v151 row_half_mirror row_mask:0xf bank_mask:0xf bound_ctrl:1
	v_pk_fma_f32 v[106:107], v[124:125], v[122:123], v[106:107] op_sel:[0,1,0]
	v_add_f32_dpp v148, v148, v148 row_mirror row_mask:0xf bank_mask:0xf bound_ctrl:1
	v_add_f32_dpp v149, v149, v149 row_mirror row_mask:0xf bank_mask:0xf bound_ctrl:1
	v_add_f32_dpp v150, v150, v150 row_mirror row_mask:0xf bank_mask:0xf bound_ctrl:1
	v_pk_fma_f32 v[100:101], v[148:149], v[116:117], v[100:101] op_sel_hi:[1,0,1]
	v_pk_fma_f32 v[102:103], v[148:149], v[116:117], v[102:103] op_sel:[0,1,0]
	v_pk_fma_f32 v[104:105], v[148:149], v[118:119], v[104:105] op_sel_hi:[1,0,1]
	v_pk_fma_f32 v[106:107], v[148:149], v[118:119], v[106:107] op_sel:[0,1,0]
	v_add_f32_dpp v151, v151, v151 row_mirror row_mask:0xf bank_mask:0xf bound_ctrl:1
	v_pk_fma_f32 v[152:153], v[148:149], v[126:127], v[150:151] op_sel_hi:[1,0,1]
	v_pk_fma_f32 v[152:153], v[124:125], v[126:127], v[152:153] op_sel:[0,1,0]
	v_cvt_pk_bf16_f32 v154, v152, v153
	s_waitcnt lgkmcnt(0)
	ds_read_b128 v[108:111], v156 offset:37248
	ds_read_b128 v[112:115], v156 offset:37504
	ds_read_b128 v[120:123], v156 offset:38272
	ds_read_b64 v[124:125], v157 offset:37248
	ds_read_b128 v[116:119], v156 offset:38016
	ds_read_b64 v[126:127], v158 offset:37248
	v_mov_b32_dpp v155, v154 row_shr:6 row_mask:0xf bank_mask:0xf
	v_pk_mul_f32 v[148:149], v[100:101], v[128:129] op_sel_hi:[1,0]
	v_pk_mul_f32 v[150:151], v[100:101], v[132:133] op_sel_hi:[1,0]
	v_pk_fma_f32 v[148:149], v[102:103], v[128:129], v[148:149] op_sel:[0,1,0]
	v_pk_fma_f32 v[150:151], v[102:103], v[132:133], v[150:151] op_sel:[0,1,0]
	v_pk_fma_f32 v[148:149], v[104:105], v[130:131], v[148:149] op_sel_hi:[1,0,1]
	v_pk_fma_f32 v[150:151], v[104:105], v[134:135], v[150:151] op_sel_hi:[1,0,1]
	v_pk_fma_f32 v[148:149], v[106:107], v[130:131], v[148:149] op_sel:[0,1,0]
	v_pk_fma_f32 v[150:151], v[106:107], v[134:135], v[150:151] op_sel:[0,1,0]
	v_pk_fma_f32 v[100:101], v[144:145], v[140:141], v[100:101] op_sel_hi:[1,0,1]
	v_add_f32_dpp v148, v148, v148 quad_perm:[1,0,3,2] row_mask:0xf bank_mask:0xf bound_ctrl:1
	v_add_f32_dpp v149, v149, v149 quad_perm:[1,0,3,2] row_mask:0xf bank_mask:0xf bound_ctrl:1
	v_add_f32_dpp v150, v150, v150 quad_perm:[1,0,3,2] row_mask:0xf bank_mask:0xf bound_ctrl:1
	v_add_f32_dpp v151, v151, v151 quad_perm:[1,0,3,2] row_mask:0xf bank_mask:0xf bound_ctrl:1
	v_pk_fma_f32 v[102:103], v[144:145], v[140:141], v[102:103] op_sel:[0,1,0]
	v_add_f32_dpp v148, v148, v148 quad_perm:[2,3,0,1] row_mask:0xf bank_mask:0xf bound_ctrl:1
	v_add_f32_dpp v149, v149, v149 quad_perm:[2,3,0,1] row_mask:0xf bank_mask:0xf bound_ctrl:1
	v_add_f32_dpp v150, v150, v150 quad_perm:[2,3,0,1] row_mask:0xf bank_mask:0xf bound_ctrl:1
	v_add_f32_dpp v151, v151, v151 quad_perm:[2,3,0,1] row_mask:0xf bank_mask:0xf bound_ctrl:1
	v_pk_fma_f32 v[104:105], v[144:145], v[142:143], v[104:105] op_sel_hi:[1,0,1]
	v_add_f32_dpp v148, v148, v148 row_half_mirror row_mask:0xf bank_mask:0xf bound_ctrl:1
	v_add_f32_dpp v149, v149, v149 row_half_mirror row_mask:0xf bank_mask:0xf bound_ctrl:1
	v_add_f32_dpp v150, v150, v150 row_half_mirror row_mask:0xf bank_mask:0xf bound_ctrl:1
	v_add_f32_dpp v151, v151, v151 row_half_mirror row_mask:0xf bank_mask:0xf bound_ctrl:1
	v_pk_fma_f32 v[106:107], v[144:145], v[142:143], v[106:107] op_sel:[0,1,0]
	v_add_f32_dpp v148, v148, v148 row_mirror row_mask:0xf bank_mask:0xf bound_ctrl:1
	v_add_f32_dpp v149, v149, v149 row_mirror row_mask:0xf bank_mask:0xf bound_ctrl:1
	v_add_f32_dpp v150, v150, v150 row_mirror row_mask:0xf bank_mask:0xf bound_ctrl:1
	v_pk_fma_f32 v[100:101], v[148:149], v[136:137], v[100:101] op_sel_hi:[1,0,1]
	v_pk_fma_f32 v[102:103], v[148:149], v[136:137], v[102:103] op_sel:[0,1,0]
	v_pk_fma_f32 v[104:105], v[148:149], v[138:139], v[104:105] op_sel_hi:[1,0,1]
	v_pk_fma_f32 v[106:107], v[148:149], v[138:139], v[106:107] op_sel:[0,1,0]
	v_add_f32_dpp v151, v151, v151 row_mirror row_mask:0xf bank_mask:0xf bound_ctrl:1
	v_pk_fma_f32 v[152:153], v[148:149], v[146:147], v[150:151] op_sel_hi:[1,0,1]
	v_pk_fma_f32 v[152:153], v[144:145], v[146:147], v[152:153] op_sel:[0,1,0]
	v_cvt_pk_bf16_f32 v154, v152, v153
	s_waitcnt lgkmcnt(0)
	ds_read_b128 v[128:131], v156 offset:38800
	ds_read_b128 v[132:135], v156 offset:39056
	ds_read_b128 v[140:143], v156 offset:39824
	ds_read_b64 v[144:145], v157 offset:38800
	ds_read_b128 v[136:139], v156 offset:39568
	ds_read_b64 v[146:147], v158 offset:38800
	v_mov_b32_dpp v155, v154 row_shr:7 row_mask:0xf bank_mask:0xf
	v_pk_mul_f32 v[148:149], v[100:101], v[108:109] op_sel_hi:[1,0]
	v_pk_mul_f32 v[150:151], v[100:101], v[112:113] op_sel_hi:[1,0]
	v_pk_fma_f32 v[148:149], v[102:103], v[108:109], v[148:149] op_sel:[0,1,0]
	v_pk_fma_f32 v[150:151], v[102:103], v[112:113], v[150:151] op_sel:[0,1,0]
	v_pk_fma_f32 v[148:149], v[104:105], v[110:111], v[148:149] op_sel_hi:[1,0,1]
	v_pk_fma_f32 v[150:151], v[104:105], v[114:115], v[150:151] op_sel_hi:[1,0,1]
	v_pk_fma_f32 v[148:149], v[106:107], v[110:111], v[148:149] op_sel:[0,1,0]
	v_pk_fma_f32 v[150:151], v[106:107], v[114:115], v[150:151] op_sel:[0,1,0]
	v_pk_fma_f32 v[100:101], v[124:125], v[120:121], v[100:101] op_sel_hi:[1,0,1]
	v_add_f32_dpp v148, v148, v148 quad_perm:[1,0,3,2] row_mask:0xf bank_mask:0xf bound_ctrl:1
	v_add_f32_dpp v149, v149, v149 quad_perm:[1,0,3,2] row_mask:0xf bank_mask:0xf bound_ctrl:1
	v_add_f32_dpp v150, v150, v150 quad_perm:[1,0,3,2] row_mask:0xf bank_mask:0xf bound_ctrl:1
	v_add_f32_dpp v151, v151, v151 quad_perm:[1,0,3,2] row_mask:0xf bank_mask:0xf bound_ctrl:1
	v_pk_fma_f32 v[102:103], v[124:125], v[120:121], v[102:103] op_sel:[0,1,0]
	v_add_f32_dpp v148, v148, v148 quad_perm:[2,3,0,1] row_mask:0xf bank_mask:0xf bound_ctrl:1
	v_add_f32_dpp v149, v149, v149 quad_perm:[2,3,0,1] row_mask:0xf bank_mask:0xf bound_ctrl:1
	v_add_f32_dpp v150, v150, v150 quad_perm:[2,3,0,1] row_mask:0xf bank_mask:0xf bound_ctrl:1
	v_add_f32_dpp v151, v151, v151 quad_perm:[2,3,0,1] row_mask:0xf bank_mask:0xf bound_ctrl:1
	v_pk_fma_f32 v[104:105], v[124:125], v[122:123], v[104:105] op_sel_hi:[1,0,1]
	v_add_f32_dpp v148, v148, v148 row_half_mirror row_mask:0xf bank_mask:0xf bound_ctrl:1
	v_add_f32_dpp v149, v149, v149 row_half_mirror row_mask:0xf bank_mask:0xf bound_ctrl:1
	v_add_f32_dpp v150, v150, v150 row_half_mirror row_mask:0xf bank_mask:0xf bound_ctrl:1
	v_add_f32_dpp v151, v151, v151 row_half_mirror row_mask:0xf bank_mask:0xf bound_ctrl:1
	v_pk_fma_f32 v[106:107], v[124:125], v[122:123], v[106:107] op_sel:[0,1,0]
	v_add_f32_dpp v148, v148, v148 row_mirror row_mask:0xf bank_mask:0xf bound_ctrl:1
	v_add_f32_dpp v149, v149, v149 row_mirror row_mask:0xf bank_mask:0xf bound_ctrl:1
	v_add_f32_dpp v150, v150, v150 row_mirror row_mask:0xf bank_mask:0xf bound_ctrl:1
	v_pk_fma_f32 v[100:101], v[148:149], v[116:117], v[100:101] op_sel_hi:[1,0,1]
	v_pk_fma_f32 v[102:103], v[148:149], v[116:117], v[102:103] op_sel:[0,1,0]
	v_pk_fma_f32 v[104:105], v[148:149], v[118:119], v[104:105] op_sel_hi:[1,0,1]
	v_pk_fma_f32 v[106:107], v[148:149], v[118:119], v[106:107] op_sel:[0,1,0]
	v_add_f32_dpp v151, v151, v151 row_mirror row_mask:0xf bank_mask:0xf bound_ctrl:1
	v_pk_fma_f32 v[152:153], v[148:149], v[126:127], v[150:151] op_sel_hi:[1,0,1]
	v_pk_fma_f32 v[152:153], v[124:125], v[126:127], v[152:153] op_sel:[0,1,0]
	v_cvt_pk_bf16_f32 v154, v152, v153
	s_waitcnt lgkmcnt(0)
	ds_read_b128 v[108:111], v156 offset:40352
	ds_read_b128 v[112:115], v156 offset:40608
	ds_read_b128 v[120:123], v156 offset:41376
	ds_read_b64 v[124:125], v157 offset:40352
	ds_read_b128 v[116:119], v156 offset:41120
	ds_read_b64 v[126:127], v158 offset:40352
	v_mov_b32_dpp v155, v154 row_shr:8 row_mask:0xf bank_mask:0xf
	v_pk_mul_f32 v[148:149], v[100:101], v[128:129] op_sel_hi:[1,0]
	v_pk_mul_f32 v[150:151], v[100:101], v[132:133] op_sel_hi:[1,0]
	v_pk_fma_f32 v[148:149], v[102:103], v[128:129], v[148:149] op_sel:[0,1,0]
	v_pk_fma_f32 v[150:151], v[102:103], v[132:133], v[150:151] op_sel:[0,1,0]
	v_pk_fma_f32 v[148:149], v[104:105], v[130:131], v[148:149] op_sel_hi:[1,0,1]
	v_pk_fma_f32 v[150:151], v[104:105], v[134:135], v[150:151] op_sel_hi:[1,0,1]
	v_pk_fma_f32 v[148:149], v[106:107], v[130:131], v[148:149] op_sel:[0,1,0]
	v_pk_fma_f32 v[150:151], v[106:107], v[134:135], v[150:151] op_sel:[0,1,0]
	v_pk_fma_f32 v[100:101], v[144:145], v[140:141], v[100:101] op_sel_hi:[1,0,1]
	v_add_f32_dpp v148, v148, v148 quad_perm:[1,0,3,2] row_mask:0xf bank_mask:0xf bound_ctrl:1
	v_add_f32_dpp v149, v149, v149 quad_perm:[1,0,3,2] row_mask:0xf bank_mask:0xf bound_ctrl:1
	v_add_f32_dpp v150, v150, v150 quad_perm:[1,0,3,2] row_mask:0xf bank_mask:0xf bound_ctrl:1
	v_add_f32_dpp v151, v151, v151 quad_perm:[1,0,3,2] row_mask:0xf bank_mask:0xf bound_ctrl:1
	v_pk_fma_f32 v[102:103], v[144:145], v[140:141], v[102:103] op_sel:[0,1,0]
	v_add_f32_dpp v148, v148, v148 quad_perm:[2,3,0,1] row_mask:0xf bank_mask:0xf bound_ctrl:1
	v_add_f32_dpp v149, v149, v149 quad_perm:[2,3,0,1] row_mask:0xf bank_mask:0xf bound_ctrl:1
	v_add_f32_dpp v150, v150, v150 quad_perm:[2,3,0,1] row_mask:0xf bank_mask:0xf bound_ctrl:1
	v_add_f32_dpp v151, v151, v151 quad_perm:[2,3,0,1] row_mask:0xf bank_mask:0xf bound_ctrl:1
	v_pk_fma_f32 v[104:105], v[144:145], v[142:143], v[104:105] op_sel_hi:[1,0,1]
	v_add_f32_dpp v148, v148, v148 row_half_mirror row_mask:0xf bank_mask:0xf bound_ctrl:1
	v_add_f32_dpp v149, v149, v149 row_half_mirror row_mask:0xf bank_mask:0xf bound_ctrl:1
	v_add_f32_dpp v150, v150, v150 row_half_mirror row_mask:0xf bank_mask:0xf bound_ctrl:1
	v_add_f32_dpp v151, v151, v151 row_half_mirror row_mask:0xf bank_mask:0xf bound_ctrl:1
	v_pk_fma_f32 v[106:107], v[144:145], v[142:143], v[106:107] op_sel:[0,1,0]
	v_add_f32_dpp v148, v148, v148 row_mirror row_mask:0xf bank_mask:0xf bound_ctrl:1
	v_add_f32_dpp v149, v149, v149 row_mirror row_mask:0xf bank_mask:0xf bound_ctrl:1
	v_add_f32_dpp v150, v150, v150 row_mirror row_mask:0xf bank_mask:0xf bound_ctrl:1
	v_pk_fma_f32 v[100:101], v[148:149], v[136:137], v[100:101] op_sel_hi:[1,0,1]
	v_pk_fma_f32 v[102:103], v[148:149], v[136:137], v[102:103] op_sel:[0,1,0]
	v_pk_fma_f32 v[104:105], v[148:149], v[138:139], v[104:105] op_sel_hi:[1,0,1]
	v_pk_fma_f32 v[106:107], v[148:149], v[138:139], v[106:107] op_sel:[0,1,0]
	v_add_f32_dpp v151, v151, v151 row_mirror row_mask:0xf bank_mask:0xf bound_ctrl:1
	v_pk_fma_f32 v[152:153], v[148:149], v[146:147], v[150:151] op_sel_hi:[1,0,1]
	v_pk_fma_f32 v[152:153], v[144:145], v[146:147], v[152:153] op_sel:[0,1,0]
	v_cvt_pk_bf16_f32 v154, v152, v153
	s_waitcnt lgkmcnt(0)
	ds_read_b128 v[128:131], v156 offset:41904
	ds_read_b128 v[132:135], v156 offset:42160
	ds_read_b128 v[140:143], v156 offset:42928
	ds_read_b64 v[144:145], v157 offset:41904
	ds_read_b128 v[136:139], v156 offset:42672
	ds_read_b64 v[146:147], v158 offset:41904
	v_mov_b32_dpp v155, v154 row_shr:9 row_mask:0xf bank_mask:0xf
	v_pk_mul_f32 v[148:149], v[100:101], v[108:109] op_sel_hi:[1,0]
	v_pk_mul_f32 v[150:151], v[100:101], v[112:113] op_sel_hi:[1,0]
	v_pk_fma_f32 v[148:149], v[102:103], v[108:109], v[148:149] op_sel:[0,1,0]
	v_pk_fma_f32 v[150:151], v[102:103], v[112:113], v[150:151] op_sel:[0,1,0]
	v_pk_fma_f32 v[148:149], v[104:105], v[110:111], v[148:149] op_sel_hi:[1,0,1]
	v_pk_fma_f32 v[150:151], v[104:105], v[114:115], v[150:151] op_sel_hi:[1,0,1]
	v_pk_fma_f32 v[148:149], v[106:107], v[110:111], v[148:149] op_sel:[0,1,0]
	v_pk_fma_f32 v[150:151], v[106:107], v[114:115], v[150:151] op_sel:[0,1,0]
	v_pk_fma_f32 v[100:101], v[124:125], v[120:121], v[100:101] op_sel_hi:[1,0,1]
	v_add_f32_dpp v148, v148, v148 quad_perm:[1,0,3,2] row_mask:0xf bank_mask:0xf bound_ctrl:1
	v_add_f32_dpp v149, v149, v149 quad_perm:[1,0,3,2] row_mask:0xf bank_mask:0xf bound_ctrl:1
	v_add_f32_dpp v150, v150, v150 quad_perm:[1,0,3,2] row_mask:0xf bank_mask:0xf bound_ctrl:1
	v_add_f32_dpp v151, v151, v151 quad_perm:[1,0,3,2] row_mask:0xf bank_mask:0xf bound_ctrl:1
	v_pk_fma_f32 v[102:103], v[124:125], v[120:121], v[102:103] op_sel:[0,1,0]
	v_add_f32_dpp v148, v148, v148 quad_perm:[2,3,0,1] row_mask:0xf bank_mask:0xf bound_ctrl:1
	v_add_f32_dpp v149, v149, v149 quad_perm:[2,3,0,1] row_mask:0xf bank_mask:0xf bound_ctrl:1
	v_add_f32_dpp v150, v150, v150 quad_perm:[2,3,0,1] row_mask:0xf bank_mask:0xf bound_ctrl:1
	v_add_f32_dpp v151, v151, v151 quad_perm:[2,3,0,1] row_mask:0xf bank_mask:0xf bound_ctrl:1
	v_pk_fma_f32 v[104:105], v[124:125], v[122:123], v[104:105] op_sel_hi:[1,0,1]
	v_add_f32_dpp v148, v148, v148 row_half_mirror row_mask:0xf bank_mask:0xf bound_ctrl:1
	v_add_f32_dpp v149, v149, v149 row_half_mirror row_mask:0xf bank_mask:0xf bound_ctrl:1
	v_add_f32_dpp v150, v150, v150 row_half_mirror row_mask:0xf bank_mask:0xf bound_ctrl:1
	v_add_f32_dpp v151, v151, v151 row_half_mirror row_mask:0xf bank_mask:0xf bound_ctrl:1
	v_pk_fma_f32 v[106:107], v[124:125], v[122:123], v[106:107] op_sel:[0,1,0]
	v_add_f32_dpp v148, v148, v148 row_mirror row_mask:0xf bank_mask:0xf bound_ctrl:1
	v_add_f32_dpp v149, v149, v149 row_mirror row_mask:0xf bank_mask:0xf bound_ctrl:1
	v_add_f32_dpp v150, v150, v150 row_mirror row_mask:0xf bank_mask:0xf bound_ctrl:1
	v_pk_fma_f32 v[100:101], v[148:149], v[116:117], v[100:101] op_sel_hi:[1,0,1]
	v_pk_fma_f32 v[102:103], v[148:149], v[116:117], v[102:103] op_sel:[0,1,0]
	v_pk_fma_f32 v[104:105], v[148:149], v[118:119], v[104:105] op_sel_hi:[1,0,1]
	v_pk_fma_f32 v[106:107], v[148:149], v[118:119], v[106:107] op_sel:[0,1,0]
	v_add_f32_dpp v151, v151, v151 row_mirror row_mask:0xf bank_mask:0xf bound_ctrl:1
	v_pk_fma_f32 v[152:153], v[148:149], v[126:127], v[150:151] op_sel_hi:[1,0,1]
	v_pk_fma_f32 v[152:153], v[124:125], v[126:127], v[152:153] op_sel:[0,1,0]
	v_cvt_pk_bf16_f32 v154, v152, v153
	s_waitcnt lgkmcnt(0)
	ds_read_b128 v[108:111], v156 offset:43456
	ds_read_b128 v[112:115], v156 offset:43712
	ds_read_b128 v[120:123], v156 offset:44480
	ds_read_b64 v[124:125], v157 offset:43456
	ds_read_b128 v[116:119], v156 offset:44224
	ds_read_b64 v[126:127], v158 offset:43456
	v_mov_b32_dpp v155, v154 row_shr:10 row_mask:0xf bank_mask:0xf
	v_pk_mul_f32 v[148:149], v[100:101], v[128:129] op_sel_hi:[1,0]
	v_pk_mul_f32 v[150:151], v[100:101], v[132:133] op_sel_hi:[1,0]
	v_pk_fma_f32 v[148:149], v[102:103], v[128:129], v[148:149] op_sel:[0,1,0]
	v_pk_fma_f32 v[150:151], v[102:103], v[132:133], v[150:151] op_sel:[0,1,0]
	v_pk_fma_f32 v[148:149], v[104:105], v[130:131], v[148:149] op_sel_hi:[1,0,1]
	v_pk_fma_f32 v[150:151], v[104:105], v[134:135], v[150:151] op_sel_hi:[1,0,1]
	v_pk_fma_f32 v[148:149], v[106:107], v[130:131], v[148:149] op_sel:[0,1,0]
	v_pk_fma_f32 v[150:151], v[106:107], v[134:135], v[150:151] op_sel:[0,1,0]
	v_pk_fma_f32 v[100:101], v[144:145], v[140:141], v[100:101] op_sel_hi:[1,0,1]
	v_add_f32_dpp v148, v148, v148 quad_perm:[1,0,3,2] row_mask:0xf bank_mask:0xf bound_ctrl:1
	v_add_f32_dpp v149, v149, v149 quad_perm:[1,0,3,2] row_mask:0xf bank_mask:0xf bound_ctrl:1
	v_add_f32_dpp v150, v150, v150 quad_perm:[1,0,3,2] row_mask:0xf bank_mask:0xf bound_ctrl:1
	v_add_f32_dpp v151, v151, v151 quad_perm:[1,0,3,2] row_mask:0xf bank_mask:0xf bound_ctrl:1
	v_pk_fma_f32 v[102:103], v[144:145], v[140:141], v[102:103] op_sel:[0,1,0]
	v_add_f32_dpp v148, v148, v148 quad_perm:[2,3,0,1] row_mask:0xf bank_mask:0xf bound_ctrl:1
	v_add_f32_dpp v149, v149, v149 quad_perm:[2,3,0,1] row_mask:0xf bank_mask:0xf bound_ctrl:1
	v_add_f32_dpp v150, v150, v150 quad_perm:[2,3,0,1] row_mask:0xf bank_mask:0xf bound_ctrl:1
	v_add_f32_dpp v151, v151, v151 quad_perm:[2,3,0,1] row_mask:0xf bank_mask:0xf bound_ctrl:1
	v_pk_fma_f32 v[104:105], v[144:145], v[142:143], v[104:105] op_sel_hi:[1,0,1]
	v_add_f32_dpp v148, v148, v148 row_half_mirror row_mask:0xf bank_mask:0xf bound_ctrl:1
	v_add_f32_dpp v149, v149, v149 row_half_mirror row_mask:0xf bank_mask:0xf bound_ctrl:1
	v_add_f32_dpp v150, v150, v150 row_half_mirror row_mask:0xf bank_mask:0xf bound_ctrl:1
	v_add_f32_dpp v151, v151, v151 row_half_mirror row_mask:0xf bank_mask:0xf bound_ctrl:1
	v_pk_fma_f32 v[106:107], v[144:145], v[142:143], v[106:107] op_sel:[0,1,0]
	v_add_f32_dpp v148, v148, v148 row_mirror row_mask:0xf bank_mask:0xf bound_ctrl:1
	v_add_f32_dpp v149, v149, v149 row_mirror row_mask:0xf bank_mask:0xf bound_ctrl:1
	v_add_f32_dpp v150, v150, v150 row_mirror row_mask:0xf bank_mask:0xf bound_ctrl:1
	v_pk_fma_f32 v[100:101], v[148:149], v[136:137], v[100:101] op_sel_hi:[1,0,1]
	v_pk_fma_f32 v[102:103], v[148:149], v[136:137], v[102:103] op_sel:[0,1,0]
	v_pk_fma_f32 v[104:105], v[148:149], v[138:139], v[104:105] op_sel_hi:[1,0,1]
	v_pk_fma_f32 v[106:107], v[148:149], v[138:139], v[106:107] op_sel:[0,1,0]
	v_add_f32_dpp v151, v151, v151 row_mirror row_mask:0xf bank_mask:0xf bound_ctrl:1
	v_pk_fma_f32 v[152:153], v[148:149], v[146:147], v[150:151] op_sel_hi:[1,0,1]
	v_pk_fma_f32 v[152:153], v[144:145], v[146:147], v[152:153] op_sel:[0,1,0]
	v_cvt_pk_bf16_f32 v154, v152, v153
	s_waitcnt lgkmcnt(0)
	ds_read_b128 v[128:131], v156 offset:45008
	ds_read_b128 v[132:135], v156 offset:45264
	ds_read_b128 v[140:143], v156 offset:46032
	ds_read_b64 v[144:145], v157 offset:45008
	ds_read_b128 v[136:139], v156 offset:45776
	ds_read_b64 v[146:147], v158 offset:45008
	v_mov_b32_dpp v155, v154 row_shr:11 row_mask:0xf bank_mask:0xf
	v_pk_mul_f32 v[148:149], v[100:101], v[108:109] op_sel_hi:[1,0]
	v_pk_mul_f32 v[150:151], v[100:101], v[112:113] op_sel_hi:[1,0]
	v_pk_fma_f32 v[148:149], v[102:103], v[108:109], v[148:149] op_sel:[0,1,0]
	v_pk_fma_f32 v[150:151], v[102:103], v[112:113], v[150:151] op_sel:[0,1,0]
	v_pk_fma_f32 v[148:149], v[104:105], v[110:111], v[148:149] op_sel_hi:[1,0,1]
	v_pk_fma_f32 v[150:151], v[104:105], v[114:115], v[150:151] op_sel_hi:[1,0,1]
	v_pk_fma_f32 v[148:149], v[106:107], v[110:111], v[148:149] op_sel:[0,1,0]
	v_pk_fma_f32 v[150:151], v[106:107], v[114:115], v[150:151] op_sel:[0,1,0]
	v_pk_fma_f32 v[100:101], v[124:125], v[120:121], v[100:101] op_sel_hi:[1,0,1]
	v_add_f32_dpp v148, v148, v148 quad_perm:[1,0,3,2] row_mask:0xf bank_mask:0xf bound_ctrl:1
	v_add_f32_dpp v149, v149, v149 quad_perm:[1,0,3,2] row_mask:0xf bank_mask:0xf bound_ctrl:1
	v_add_f32_dpp v150, v150, v150 quad_perm:[1,0,3,2] row_mask:0xf bank_mask:0xf bound_ctrl:1
	v_add_f32_dpp v151, v151, v151 quad_perm:[1,0,3,2] row_mask:0xf bank_mask:0xf bound_ctrl:1
	v_pk_fma_f32 v[102:103], v[124:125], v[120:121], v[102:103] op_sel:[0,1,0]
	v_add_f32_dpp v148, v148, v148 quad_perm:[2,3,0,1] row_mask:0xf bank_mask:0xf bound_ctrl:1
	v_add_f32_dpp v149, v149, v149 quad_perm:[2,3,0,1] row_mask:0xf bank_mask:0xf bound_ctrl:1
	v_add_f32_dpp v150, v150, v150 quad_perm:[2,3,0,1] row_mask:0xf bank_mask:0xf bound_ctrl:1
	v_add_f32_dpp v151, v151, v151 quad_perm:[2,3,0,1] row_mask:0xf bank_mask:0xf bound_ctrl:1
	v_pk_fma_f32 v[104:105], v[124:125], v[122:123], v[104:105] op_sel_hi:[1,0,1]
	v_add_f32_dpp v148, v148, v148 row_half_mirror row_mask:0xf bank_mask:0xf bound_ctrl:1
	v_add_f32_dpp v149, v149, v149 row_half_mirror row_mask:0xf bank_mask:0xf bound_ctrl:1
	v_add_f32_dpp v150, v150, v150 row_half_mirror row_mask:0xf bank_mask:0xf bound_ctrl:1
	v_add_f32_dpp v151, v151, v151 row_half_mirror row_mask:0xf bank_mask:0xf bound_ctrl:1
	v_pk_fma_f32 v[106:107], v[124:125], v[122:123], v[106:107] op_sel:[0,1,0]
	v_add_f32_dpp v148, v148, v148 row_mirror row_mask:0xf bank_mask:0xf bound_ctrl:1
	v_add_f32_dpp v149, v149, v149 row_mirror row_mask:0xf bank_mask:0xf bound_ctrl:1
	v_add_f32_dpp v150, v150, v150 row_mirror row_mask:0xf bank_mask:0xf bound_ctrl:1
	v_pk_fma_f32 v[100:101], v[148:149], v[116:117], v[100:101] op_sel_hi:[1,0,1]
	v_pk_fma_f32 v[102:103], v[148:149], v[116:117], v[102:103] op_sel:[0,1,0]
	v_pk_fma_f32 v[104:105], v[148:149], v[118:119], v[104:105] op_sel_hi:[1,0,1]
	v_pk_fma_f32 v[106:107], v[148:149], v[118:119], v[106:107] op_sel:[0,1,0]
	v_add_f32_dpp v151, v151, v151 row_mirror row_mask:0xf bank_mask:0xf bound_ctrl:1
	v_pk_fma_f32 v[152:153], v[148:149], v[126:127], v[150:151] op_sel_hi:[1,0,1]
	v_pk_fma_f32 v[152:153], v[124:125], v[126:127], v[152:153] op_sel:[0,1,0]
	v_cvt_pk_bf16_f32 v154, v152, v153
	s_waitcnt lgkmcnt(0)
	ds_read_b128 v[108:111], v156 offset:46560
	ds_read_b128 v[112:115], v156 offset:46816
	ds_read_b128 v[120:123], v156 offset:47584
	ds_read_b64 v[124:125], v157 offset:46560
	ds_read_b128 v[116:119], v156 offset:47328
	ds_read_b64 v[126:127], v158 offset:46560
	v_mov_b32_dpp v155, v154 row_shr:12 row_mask:0xf bank_mask:0xf
	v_pk_mul_f32 v[148:149], v[100:101], v[128:129] op_sel_hi:[1,0]
	v_pk_mul_f32 v[150:151], v[100:101], v[132:133] op_sel_hi:[1,0]
	v_pk_fma_f32 v[148:149], v[102:103], v[128:129], v[148:149] op_sel:[0,1,0]
	v_pk_fma_f32 v[150:151], v[102:103], v[132:133], v[150:151] op_sel:[0,1,0]
	v_pk_fma_f32 v[148:149], v[104:105], v[130:131], v[148:149] op_sel_hi:[1,0,1]
	v_pk_fma_f32 v[150:151], v[104:105], v[134:135], v[150:151] op_sel_hi:[1,0,1]
	v_pk_fma_f32 v[148:149], v[106:107], v[130:131], v[148:149] op_sel:[0,1,0]
	v_pk_fma_f32 v[150:151], v[106:107], v[134:135], v[150:151] op_sel:[0,1,0]
	v_pk_fma_f32 v[100:101], v[144:145], v[140:141], v[100:101] op_sel_hi:[1,0,1]
	v_add_f32_dpp v148, v148, v148 quad_perm:[1,0,3,2] row_mask:0xf bank_mask:0xf bound_ctrl:1
	v_add_f32_dpp v149, v149, v149 quad_perm:[1,0,3,2] row_mask:0xf bank_mask:0xf bound_ctrl:1
	v_add_f32_dpp v150, v150, v150 quad_perm:[1,0,3,2] row_mask:0xf bank_mask:0xf bound_ctrl:1
	v_add_f32_dpp v151, v151, v151 quad_perm:[1,0,3,2] row_mask:0xf bank_mask:0xf bound_ctrl:1
	v_pk_fma_f32 v[102:103], v[144:145], v[140:141], v[102:103] op_sel:[0,1,0]
	v_add_f32_dpp v148, v148, v148 quad_perm:[2,3,0,1] row_mask:0xf bank_mask:0xf bound_ctrl:1
	v_add_f32_dpp v149, v149, v149 quad_perm:[2,3,0,1] row_mask:0xf bank_mask:0xf bound_ctrl:1
	v_add_f32_dpp v150, v150, v150 quad_perm:[2,3,0,1] row_mask:0xf bank_mask:0xf bound_ctrl:1
	v_add_f32_dpp v151, v151, v151 quad_perm:[2,3,0,1] row_mask:0xf bank_mask:0xf bound_ctrl:1
	v_pk_fma_f32 v[104:105], v[144:145], v[142:143], v[104:105] op_sel_hi:[1,0,1]
	v_add_f32_dpp v148, v148, v148 row_half_mirror row_mask:0xf bank_mask:0xf bound_ctrl:1
	v_add_f32_dpp v149, v149, v149 row_half_mirror row_mask:0xf bank_mask:0xf bound_ctrl:1
	v_add_f32_dpp v150, v150, v150 row_half_mirror row_mask:0xf bank_mask:0xf bound_ctrl:1
	v_add_f32_dpp v151, v151, v151 row_half_mirror row_mask:0xf bank_mask:0xf bound_ctrl:1
	v_pk_fma_f32 v[106:107], v[144:145], v[142:143], v[106:107] op_sel:[0,1,0]
	v_add_f32_dpp v148, v148, v148 row_mirror row_mask:0xf bank_mask:0xf bound_ctrl:1
	v_add_f32_dpp v149, v149, v149 row_mirror row_mask:0xf bank_mask:0xf bound_ctrl:1
	v_add_f32_dpp v150, v150, v150 row_mirror row_mask:0xf bank_mask:0xf bound_ctrl:1
	v_pk_fma_f32 v[100:101], v[148:149], v[136:137], v[100:101] op_sel_hi:[1,0,1]
	v_pk_fma_f32 v[102:103], v[148:149], v[136:137], v[102:103] op_sel:[0,1,0]
	v_pk_fma_f32 v[104:105], v[148:149], v[138:139], v[104:105] op_sel_hi:[1,0,1]
	v_pk_fma_f32 v[106:107], v[148:149], v[138:139], v[106:107] op_sel:[0,1,0]
	v_add_f32_dpp v151, v151, v151 row_mirror row_mask:0xf bank_mask:0xf bound_ctrl:1
	v_pk_fma_f32 v[152:153], v[148:149], v[146:147], v[150:151] op_sel_hi:[1,0,1]
	v_pk_fma_f32 v[152:153], v[144:145], v[146:147], v[152:153] op_sel:[0,1,0]
	v_cvt_pk_bf16_f32 v154, v152, v153
	s_waitcnt lgkmcnt(0)
	ds_read_b128 v[128:131], v156 offset:48112
	ds_read_b128 v[132:135], v156 offset:48368
	ds_read_b128 v[140:143], v156 offset:49136
	ds_read_b64 v[144:145], v157 offset:48112
	ds_read_b128 v[136:139], v156 offset:48880
	ds_read_b64 v[146:147], v158 offset:48112
	v_mov_b32_dpp v155, v154 row_shr:13 row_mask:0xf bank_mask:0xf
	v_pk_mul_f32 v[148:149], v[100:101], v[108:109] op_sel_hi:[1,0]
	v_pk_mul_f32 v[150:151], v[100:101], v[112:113] op_sel_hi:[1,0]
	v_pk_fma_f32 v[148:149], v[102:103], v[108:109], v[148:149] op_sel:[0,1,0]
	v_pk_fma_f32 v[150:151], v[102:103], v[112:113], v[150:151] op_sel:[0,1,0]
	v_pk_fma_f32 v[148:149], v[104:105], v[110:111], v[148:149] op_sel_hi:[1,0,1]
	v_pk_fma_f32 v[150:151], v[104:105], v[114:115], v[150:151] op_sel_hi:[1,0,1]
	v_pk_fma_f32 v[148:149], v[106:107], v[110:111], v[148:149] op_sel:[0,1,0]
	v_pk_fma_f32 v[150:151], v[106:107], v[114:115], v[150:151] op_sel:[0,1,0]
	v_pk_fma_f32 v[100:101], v[124:125], v[120:121], v[100:101] op_sel_hi:[1,0,1]
	v_add_f32_dpp v148, v148, v148 quad_perm:[1,0,3,2] row_mask:0xf bank_mask:0xf bound_ctrl:1
	v_add_f32_dpp v149, v149, v149 quad_perm:[1,0,3,2] row_mask:0xf bank_mask:0xf bound_ctrl:1
	v_add_f32_dpp v150, v150, v150 quad_perm:[1,0,3,2] row_mask:0xf bank_mask:0xf bound_ctrl:1
	v_add_f32_dpp v151, v151, v151 quad_perm:[1,0,3,2] row_mask:0xf bank_mask:0xf bound_ctrl:1
	v_pk_fma_f32 v[102:103], v[124:125], v[120:121], v[102:103] op_sel:[0,1,0]
	v_add_f32_dpp v148, v148, v148 quad_perm:[2,3,0,1] row_mask:0xf bank_mask:0xf bound_ctrl:1
	v_add_f32_dpp v149, v149, v149 quad_perm:[2,3,0,1] row_mask:0xf bank_mask:0xf bound_ctrl:1
	v_add_f32_dpp v150, v150, v150 quad_perm:[2,3,0,1] row_mask:0xf bank_mask:0xf bound_ctrl:1
	v_add_f32_dpp v151, v151, v151 quad_perm:[2,3,0,1] row_mask:0xf bank_mask:0xf bound_ctrl:1
	v_pk_fma_f32 v[104:105], v[124:125], v[122:123], v[104:105] op_sel_hi:[1,0,1]
	v_add_f32_dpp v148, v148, v148 row_half_mirror row_mask:0xf bank_mask:0xf bound_ctrl:1
	v_add_f32_dpp v149, v149, v149 row_half_mirror row_mask:0xf bank_mask:0xf bound_ctrl:1
	v_add_f32_dpp v150, v150, v150 row_half_mirror row_mask:0xf bank_mask:0xf bound_ctrl:1
	v_add_f32_dpp v151, v151, v151 row_half_mirror row_mask:0xf bank_mask:0xf bound_ctrl:1
	v_pk_fma_f32 v[106:107], v[124:125], v[122:123], v[106:107] op_sel:[0,1,0]
	v_add_f32_dpp v148, v148, v148 row_mirror row_mask:0xf bank_mask:0xf bound_ctrl:1
	v_add_f32_dpp v149, v149, v149 row_mirror row_mask:0xf bank_mask:0xf bound_ctrl:1
	v_add_f32_dpp v150, v150, v150 row_mirror row_mask:0xf bank_mask:0xf bound_ctrl:1
	v_pk_fma_f32 v[100:101], v[148:149], v[116:117], v[100:101] op_sel_hi:[1,0,1]
	v_pk_fma_f32 v[102:103], v[148:149], v[116:117], v[102:103] op_sel:[0,1,0]
	v_pk_fma_f32 v[104:105], v[148:149], v[118:119], v[104:105] op_sel_hi:[1,0,1]
	v_pk_fma_f32 v[106:107], v[148:149], v[118:119], v[106:107] op_sel:[0,1,0]
	v_add_f32_dpp v151, v151, v151 row_mirror row_mask:0xf bank_mask:0xf bound_ctrl:1
	v_pk_fma_f32 v[152:153], v[148:149], v[126:127], v[150:151] op_sel_hi:[1,0,1]
	v_pk_fma_f32 v[152:153], v[124:125], v[126:127], v[152:153] op_sel:[0,1,0]
	v_cvt_pk_bf16_f32 v154, v152, v153
	s_waitcnt lgkmcnt(0)
	ds_read_b128 v[204:207], v156 offset:48624
	s_nop 0
	v_mov_b32_dpp v155, v154 row_shr:14 row_mask:0xf bank_mask:0xf
	v_pk_mul_f32 v[148:149], v[100:101], v[128:129] op_sel_hi:[1,0]
	v_pk_mul_f32 v[150:151], v[100:101], v[132:133] op_sel_hi:[1,0]
	v_pk_fma_f32 v[148:149], v[102:103], v[128:129], v[148:149] op_sel:[0,1,0]
	v_pk_fma_f32 v[150:151], v[102:103], v[132:133], v[150:151] op_sel:[0,1,0]
	v_pk_fma_f32 v[148:149], v[104:105], v[130:131], v[148:149] op_sel_hi:[1,0,1]
	v_pk_fma_f32 v[150:151], v[104:105], v[134:135], v[150:151] op_sel_hi:[1,0,1]
	v_pk_fma_f32 v[148:149], v[106:107], v[130:131], v[148:149] op_sel:[0,1,0]
	v_pk_fma_f32 v[150:151], v[106:107], v[134:135], v[150:151] op_sel:[0,1,0]
	v_pk_fma_f32 v[100:101], v[144:145], v[140:141], v[100:101] op_sel_hi:[1,0,1]
	v_add_f32_dpp v148, v148, v148 quad_perm:[1,0,3,2] row_mask:0xf bank_mask:0xf bound_ctrl:1
	v_add_f32_dpp v149, v149, v149 quad_perm:[1,0,3,2] row_mask:0xf bank_mask:0xf bound_ctrl:1
	v_add_f32_dpp v150, v150, v150 quad_perm:[1,0,3,2] row_mask:0xf bank_mask:0xf bound_ctrl:1
	v_add_f32_dpp v151, v151, v151 quad_perm:[1,0,3,2] row_mask:0xf bank_mask:0xf bound_ctrl:1
	v_pk_fma_f32 v[102:103], v[144:145], v[140:141], v[102:103] op_sel:[0,1,0]
	v_add_f32_dpp v148, v148, v148 quad_perm:[2,3,0,1] row_mask:0xf bank_mask:0xf bound_ctrl:1
	v_add_f32_dpp v149, v149, v149 quad_perm:[2,3,0,1] row_mask:0xf bank_mask:0xf bound_ctrl:1
	v_add_f32_dpp v150, v150, v150 quad_perm:[2,3,0,1] row_mask:0xf bank_mask:0xf bound_ctrl:1
	v_add_f32_dpp v151, v151, v151 quad_perm:[2,3,0,1] row_mask:0xf bank_mask:0xf bound_ctrl:1
	v_pk_fma_f32 v[104:105], v[144:145], v[142:143], v[104:105] op_sel_hi:[1,0,1]
	v_add_f32_dpp v148, v148, v148 row_half_mirror row_mask:0xf bank_mask:0xf bound_ctrl:1
	v_add_f32_dpp v149, v149, v149 row_half_mirror row_mask:0xf bank_mask:0xf bound_ctrl:1
	v_add_f32_dpp v150, v150, v150 row_half_mirror row_mask:0xf bank_mask:0xf bound_ctrl:1
	v_add_f32_dpp v151, v151, v151 row_half_mirror row_mask:0xf bank_mask:0xf bound_ctrl:1
	v_pk_fma_f32 v[106:107], v[144:145], v[142:143], v[106:107] op_sel:[0,1,0]
	v_add_f32_dpp v148, v148, v148 row_mirror row_mask:0xf bank_mask:0xf bound_ctrl:1
	v_add_f32_dpp v149, v149, v149 row_mirror row_mask:0xf bank_mask:0xf bound_ctrl:1
	v_add_f32_dpp v150, v150, v150 row_mirror row_mask:0xf bank_mask:0xf bound_ctrl:1
	v_pk_fma_f32 v[100:101], v[148:149], v[136:137], v[100:101] op_sel_hi:[1,0,1]
	v_pk_fma_f32 v[102:103], v[148:149], v[136:137], v[102:103] op_sel:[0,1,0]
	v_pk_fma_f32 v[104:105], v[148:149], v[138:139], v[104:105] op_sel_hi:[1,0,1]
	v_pk_fma_f32 v[106:107], v[148:149], v[138:139], v[106:107] op_sel:[0,1,0]
	v_add_f32_dpp v151, v151, v151 row_mirror row_mask:0xf bank_mask:0xf bound_ctrl:1
	v_pk_fma_f32 v[152:153], v[148:149], v[146:147], v[150:151] op_sel_hi:[1,0,1]
	v_pk_fma_f32 v[152:153], v[144:145], v[146:147], v[152:153] op_sel:[0,1,0]
	v_cvt_pk_bf16_f32 v154, v152, v153
	s_waitcnt lgkmcnt(0)
	v_pk_mul_f32 v[100:101], v[100:101], v[204:205] op_sel_hi:[1,0]
	v_pk_mul_f32 v[102:103], v[102:103], v[204:205] op_sel:[0,1]
	v_pk_mul_f32 v[104:105], v[104:105], v[206:207] op_sel_hi:[1,0]
	v_pk_mul_f32 v[106:107], v[106:107], v[206:207] op_sel:[0,1]
	v_mov_b32_dpp v155, v154 row_shr:15 row_mask:0xf bank_mask:0xf
	global_store_dword v[160:161], v155, off
	s_cmp_lg_u32 s30, 63
	s_cbranch_scc1 .Lrwp_done
	v_mov_b32_e32 v14, v100
	v_mov_b32_e32 v15, v102
	v_mov_b32_e32 v16, v104
	v_mov_b32_e32 v17, v106
	v_mov_b32_e32 v10, v101
	v_mov_b32_e32 v11, v103
	v_mov_b32_e32 v12, v105
	v_mov_b32_e32 v13, v107
.Lrwp_done:
	s_branch .LBB0_1347

	.amdhsa_kernel _Z10fwd_kernel4Args
		.amdhsa_group_segment_fixed_size 0
		.amdhsa_private_segment_fixed_size 0
		.amdhsa_kernarg_size 568
		.amdhsa_user_sgpr_count 2
		.amdhsa_user_sgpr_dispatch_ptr 0
		.amdhsa_user_sgpr_queue_ptr 0
		.amdhsa_user_sgpr_kernarg_segment_ptr 1
		.amdhsa_user_sgpr_dispatch_id 0
		.amdhsa_user_sgpr_kernarg_preload_length 0
		.amdhsa_user_sgpr_kernarg_preload_offset 0
		.amdhsa_user_sgpr_private_segment_size 0
		.amdhsa_uses_dynamic_stack 0
		.amdhsa_enable_private_segment 0
		.amdhsa_system_sgpr_workgroup_id_x 1
		.amdhsa_system_sgpr_workgroup_id_y 0
		.amdhsa_system_sgpr_workgroup_id_z 0
		.amdhsa_system_sgpr_workgroup_info 0
		.amdhsa_system_vgpr_workitem_id 2
		.amdhsa_next_free_vgpr 250
		.amdhsa_next_free_sgpr 102
		.amdhsa_accum_offset 252
		.amdhsa_reserve_vcc 1
		.amdhsa_float_round_mode_32 0
		.amdhsa_float_round_mode_16_64 0
		.amdhsa_float_denorm_mode_32 3
		.amdhsa_float_denorm_mode_16_64 3
		.amdhsa_dx10_clamp 1
		.amdhsa_ieee_mode 1
		.amdhsa_fp16_overflow 0
		.amdhsa_tg_split 0
		.amdhsa_exception_fp_ieee_invalid_op 0
		.amdhsa_exception_fp_denorm_src 0
		.amdhsa_exception_fp_ieee_div_zero 0
		.amdhsa_exception_fp_ieee_overflow 0
		.amdhsa_exception_fp_ieee_underflow 0
		.amdhsa_exception_fp_ieee_inexact 0
		.amdhsa_exception_int_div_zero 0
	.end_amdhsa_kernel

amdhsa.kernels:
  - .agpr_count:     0
    .args:
      - .offset:         0
        .size:           312
        .value_kind:     by_value
      - .offset:         312
        .size:           4
        .value_kind:     hidden_block_count_x
      - .offset:         316
        .size:           4
        .value_kind:     hidden_block_count_y
      - .offset:         320
        .size:           4
        .value_kind:     hidden_block_count_z
      - .offset:         324
        .size:           2
        .value_kind:     hidden_group_size_x
      - .offset:         326
        .size:           2
        .value_kind:     hidden_group_size_y
      - .offset:         328
        .size:           2
        .value_kind:     hidden_group_size_z
      - .offset:         330
        .size:           2
        .value_kind:     hidden_remainder_x
      - .offset:         332
        .size:           2
        .value_kind:     hidden_remainder_y
      - .offset:         334
        .size:           2
        .value_kind:     hidden_remainder_z
      - .offset:         352
        .size:           8
        .value_kind:     hidden_global_offset_x
      - .offset:         360
        .size:           8
        .value_kind:     hidden_global_offset_y
      - .offset:         368
        .size:           8
        .value_kind:     hidden_global_offset_z
      - .offset:         376
        .size:           2
        .value_kind:     hidden_grid_dims
      - .offset:         400
        .size:           8
        .value_kind:     hidden_multigrid_sync_arg
      - .offset:         432
        .size:           4
        .value_kind:     hidden_dynamic_lds_size
    .group_segment_fixed_size: 0
    .kernarg_segment_align: 8
    .kernarg_segment_size: 568
    .language:       OpenCL C
    .language_version:
      - 2
      - 0
    .max_flat_workgroup_size: 512
    .name:           _Z10fwd_kernel4Args
    .private_segment_fixed_size: 0
    .sgpr_count:     108
    .sgpr_spill_count: 8
    .symbol:         _Z10fwd_kernel4Args.kd
    .uniform_work_group_size: 1
    .uses_dynamic_stack: false
    .vgpr_count:     250
    .vgpr_spill_count: 0
    .wavefront_size: 64
